# v16 plus: accumulator pairs ordered n-major (SrcA fragment fixed across four consecutive pairs) in the clean MFMA blocks
# speedup vs baseline: 1.0072x; 1.0072x over previous
.LBB0_230:
	s_add_u32 s28, s0, 0xfff00080
	s_addc_u32 s29, s1, -1
	s_add_i32 s51, 0, 0x10000
	s_cmp_eq_u32 s50, 60
	s_cselect_b32 s31, s34, s29
	s_cselect_b32 s30, s35, s28
	v_add_u32_e32 v0, s51, v179
	s_cselect_b32 s29, s27, s43
	s_cselect_b32 s28, s40, s41
	s_add_i32 s77, 0, 0x14000
	ds_read_b128 v[130:133], v0
	ds_read_b128 v[134:137], v0 offset:1024
	ds_read_b128 v[138:141], v0 offset:2048
	ds_read_b128 v[142:145], v0 offset:3072
	v_add_u32_e32 v0, s77, v179
	ds_read_b128 v[146:149], v0
	ds_read_b128 v[150:153], v0 offset:1024
	ds_read_b128 v[154:157], v0 offset:2048
	ds_read_b128 v[158:161], v0 offset:3072
	v_lshl_add_u64 v[194:195], s[0:1], 0, v[170:171]
	s_add_i32 m0, s14, 0xc000
	ds_read_b128 v[174:177], v192
	ds_read_b128 v[180:183], v192 offset:1024
	ds_read_b128 v[184:187], v192 offset:2048
	ds_read_b128 v[188:191], v192 offset:3072
	ds_read_b128 v[200:203], v192 offset:4096
	ds_read_b128 v[204:207], v192 offset:5120
	ds_read_b128 v[208:211], v192 offset:6144
	ds_read_b128 v[212:215], v192 offset:7168
	global_load_lds_dwordx4 v[194:195], off
	v_lshl_add_u64 v[194:195], s[0:1], 0, v[172:173]
	s_add_i32 m0, s14, 0xe000
	s_nop 0
	global_load_lds_dwordx4 v[194:195], off
	s_waitcnt vmcnt(8)
	s_waitcnt lgkmcnt(0)
	s_barrier
	s_waitcnt lgkmcnt(0)
	v_mfma_f32_16x16x32_bf16 v[126:129], v[130:133], v[174:177], v[126:129]
	v_mfma_f32_16x16x32_bf16 v[126:129], v[134:137], v[180:183], v[126:129]
	v_mfma_f32_16x16x32_bf16 v[110:113], v[130:133], v[184:187], v[110:113]
	v_mfma_f32_16x16x32_bf16 v[110:113], v[134:137], v[188:191], v[110:113]
	v_mfma_f32_16x16x32_bf16 v[94:97], v[130:133], v[200:203], v[94:97]
	v_mfma_f32_16x16x32_bf16 v[94:97], v[134:137], v[204:207], v[94:97]
	v_mfma_f32_16x16x32_bf16 v[78:81], v[130:133], v[208:211], v[78:81]
	v_mfma_f32_16x16x32_bf16 v[78:81], v[134:137], v[212:215], v[78:81]
	v_mfma_f32_16x16x32_bf16 v[122:125], v[138:141], v[174:177], v[122:125]
	v_mfma_f32_16x16x32_bf16 v[122:125], v[142:145], v[180:183], v[122:125]
	v_mfma_f32_16x16x32_bf16 v[106:109], v[138:141], v[184:187], v[106:109]
	v_mfma_f32_16x16x32_bf16 v[106:109], v[142:145], v[188:191], v[106:109]
	v_mfma_f32_16x16x32_bf16 v[90:93], v[138:141], v[200:203], v[90:93]
	v_mfma_f32_16x16x32_bf16 v[90:93], v[142:145], v[204:207], v[90:93]
	v_mfma_f32_16x16x32_bf16 v[74:77], v[138:141], v[208:211], v[74:77]
	v_mfma_f32_16x16x32_bf16 v[74:77], v[142:145], v[212:215], v[74:77]
	v_mfma_f32_16x16x32_bf16 v[118:121], v[146:149], v[174:177], v[118:121]
	v_mfma_f32_16x16x32_bf16 v[118:121], v[150:153], v[180:183], v[118:121]
	v_mfma_f32_16x16x32_bf16 v[102:105], v[146:149], v[184:187], v[102:105]
	v_mfma_f32_16x16x32_bf16 v[102:105], v[150:153], v[188:191], v[102:105]
	v_mfma_f32_16x16x32_bf16 v[86:89], v[146:149], v[200:203], v[86:89]
	v_mfma_f32_16x16x32_bf16 v[86:89], v[150:153], v[204:207], v[86:89]
	v_mfma_f32_16x16x32_bf16 v[70:73], v[146:149], v[208:211], v[70:73]
	v_mfma_f32_16x16x32_bf16 v[70:73], v[150:153], v[212:215], v[70:73]
	v_mfma_f32_16x16x32_bf16 v[114:117], v[154:157], v[174:177], v[114:117]
	v_mfma_f32_16x16x32_bf16 v[114:117], v[158:161], v[180:183], v[114:117]
	v_mfma_f32_16x16x32_bf16 v[98:101], v[154:157], v[184:187], v[98:101]
	v_mfma_f32_16x16x32_bf16 v[98:101], v[158:161], v[188:191], v[98:101]
	v_mfma_f32_16x16x32_bf16 v[82:85], v[154:157], v[200:203], v[82:85]
	v_mfma_f32_16x16x32_bf16 v[82:85], v[158:161], v[204:207], v[82:85]
	v_mfma_f32_16x16x32_bf16 v[66:69], v[154:157], v[208:211], v[66:69]
	v_mfma_f32_16x16x32_bf16 v[66:69], v[158:161], v[212:215], v[66:69]
	s_barrier
	s_add_i32 s51, s51, s9
	v_lshl_add_u64 v[194:195], s[28:29], 0, v[166:167]
	s_mov_b32 m0, s51
	ds_read_b128 v[174:177], v192 offset:16384
	ds_read_b128 v[180:183], v192 offset:17408
	ds_read_b128 v[184:187], v192 offset:18432
	ds_read_b128 v[188:191], v192 offset:19456
	ds_read_b128 v[200:203], v192 offset:20480
	ds_read_b128 v[204:207], v192 offset:21504
	ds_read_b128 v[208:211], v192 offset:22528
	ds_read_b128 v[212:215], v192 offset:23552
	global_load_lds_dwordx4 v[194:195], off
	s_add_i32 m0, s51, 0x2000
	s_add_u32 s80, s28, 0x100000
	v_lshl_add_u64 v[216:217], s[28:29], 0, v[162:163]
	s_addc_u32 s81, s29, 0
	s_add_i32 s51, s77, s9
	global_load_lds_dwordx4 v[216:217], off
	v_lshl_add_u64 v[218:219], s[80:81], 0, v[166:167]
	s_mov_b32 m0, s51
	v_lshl_add_u64 v[220:221], s[30:31], 0, v[164:165]
	global_load_lds_dwordx4 v[218:219], off
	v_lshl_add_u64 v[218:219], s[80:81], 0, v[162:163]
	s_add_i32 m0, s51, 0x2000
	s_nop 0
	global_load_lds_dwordx4 v[218:219], off
	v_lshl_add_u64 v[218:219], s[30:31], 0, v[168:169]
	s_mov_b32 m0, s14
	s_nop 0
	global_load_lds_dwordx4 v[218:219], off
	s_mov_b32 m0, s15
	s_nop 0
	global_load_lds_dwordx4 v[220:221], off
	s_waitcnt vmcnt(8)
	s_waitcnt lgkmcnt(0)
	s_barrier
	s_waitcnt lgkmcnt(0)
	v_mfma_f32_16x16x32_bf16 v[62:65], v[130:133], v[174:177], v[62:65]
	v_mfma_f32_16x16x32_bf16 v[62:65], v[134:137], v[180:183], v[62:65]
	v_mfma_f32_16x16x32_bf16 v[46:49], v[130:133], v[184:187], v[46:49]
	v_mfma_f32_16x16x32_bf16 v[46:49], v[134:137], v[188:191], v[46:49]
	v_mfma_f32_16x16x32_bf16 v[30:33], v[130:133], v[200:203], v[30:33]
	v_mfma_f32_16x16x32_bf16 v[30:33], v[134:137], v[204:207], v[30:33]
	v_mfma_f32_16x16x32_bf16 v[14:17], v[130:133], v[208:211], v[14:17]
	v_mfma_f32_16x16x32_bf16 v[14:17], v[134:137], v[212:215], v[14:17]
	v_mfma_f32_16x16x32_bf16 v[58:61], v[138:141], v[174:177], v[58:61]
	v_mfma_f32_16x16x32_bf16 v[58:61], v[142:145], v[180:183], v[58:61]
	v_mfma_f32_16x16x32_bf16 v[42:45], v[138:141], v[184:187], v[42:45]
	v_mfma_f32_16x16x32_bf16 v[42:45], v[142:145], v[188:191], v[42:45]
	v_mfma_f32_16x16x32_bf16 v[26:29], v[138:141], v[200:203], v[26:29]
	v_mfma_f32_16x16x32_bf16 v[26:29], v[142:145], v[204:207], v[26:29]
	v_mfma_f32_16x16x32_bf16 v[10:13], v[138:141], v[208:211], v[10:13]
	v_mfma_f32_16x16x32_bf16 v[10:13], v[142:145], v[212:215], v[10:13]
	v_mfma_f32_16x16x32_bf16 v[54:57], v[146:149], v[174:177], v[54:57]
	v_mfma_f32_16x16x32_bf16 v[54:57], v[150:153], v[180:183], v[54:57]
	v_mfma_f32_16x16x32_bf16 v[38:41], v[146:149], v[184:187], v[38:41]
	v_mfma_f32_16x16x32_bf16 v[38:41], v[150:153], v[188:191], v[38:41]
	v_mfma_f32_16x16x32_bf16 v[22:25], v[146:149], v[200:203], v[22:25]
	v_mfma_f32_16x16x32_bf16 v[22:25], v[150:153], v[204:207], v[22:25]
	v_mfma_f32_16x16x32_bf16 v[6:9], v[146:149], v[208:211], v[6:9]
	v_mfma_f32_16x16x32_bf16 v[6:9], v[150:153], v[212:215], v[6:9]
	v_mfma_f32_16x16x32_bf16 v[50:53], v[154:157], v[174:177], v[50:53]
	v_mfma_f32_16x16x32_bf16 v[50:53], v[158:161], v[180:183], v[50:53]
	v_mfma_f32_16x16x32_bf16 v[34:37], v[154:157], v[184:187], v[34:37]
	v_mfma_f32_16x16x32_bf16 v[34:37], v[158:161], v[188:191], v[34:37]
	v_mfma_f32_16x16x32_bf16 v[18:21], v[154:157], v[200:203], v[18:21]
	v_mfma_f32_16x16x32_bf16 v[18:21], v[158:161], v[204:207], v[18:21]
	v_mfma_f32_16x16x32_bf16 v[2:5], v[154:157], v[208:211], v[2:5]
	v_mfma_f32_16x16x32_bf16 v[2:5], v[158:161], v[212:215], v[2:5]
	s_barrier
	s_add_i32 s51, 0, 0x18000
	v_add_u32_e32 v0, s51, v179
	s_add_i32 s77, 0, 0x1c000
	ds_read_b128 v[130:133], v0
	ds_read_b128 v[134:137], v0 offset:1024
	ds_read_b128 v[138:141], v0 offset:2048
	ds_read_b128 v[142:145], v0 offset:3072
	v_add_u32_e32 v0, s77, v179
	ds_read_b128 v[146:149], v0
	ds_read_b128 v[150:153], v0 offset:1024
	ds_read_b128 v[154:157], v0 offset:2048
	ds_read_b128 v[158:161], v0 offset:3072
	s_add_u32 s30, s30, 0x100000
	s_addc_u32 s31, s31, 0
	s_mov_b32 m0, s52
	v_lshl_add_u64 v[222:223], s[30:31], 0, v[168:169]
	ds_read_b128 v[174:177], v192 offset:32768
	ds_read_b128 v[180:183], v192 offset:33792
	ds_read_b128 v[184:187], v192 offset:34816
	ds_read_b128 v[188:191], v192 offset:35840
	ds_read_b128 v[200:203], v192 offset:36864
	ds_read_b128 v[204:207], v192 offset:37888
	ds_read_b128 v[208:211], v192 offset:38912
	ds_read_b128 v[212:215], v192 offset:39936
	global_load_lds_dwordx4 v[222:223], off
	v_lshl_add_u64 v[222:223], s[30:31], 0, v[164:165]
	s_mov_b32 m0, s53
	s_nop 0
	global_load_lds_dwordx4 v[222:223], off
	s_waitcnt vmcnt(8)
	s_waitcnt lgkmcnt(0)
	s_barrier
	s_waitcnt lgkmcnt(0)
	v_mfma_f32_16x16x32_bf16 v[126:129], v[130:133], v[174:177], v[126:129]
	v_mfma_f32_16x16x32_bf16 v[126:129], v[134:137], v[180:183], v[126:129]
	v_mfma_f32_16x16x32_bf16 v[110:113], v[130:133], v[184:187], v[110:113]
	v_mfma_f32_16x16x32_bf16 v[110:113], v[134:137], v[188:191], v[110:113]
	v_mfma_f32_16x16x32_bf16 v[94:97], v[130:133], v[200:203], v[94:97]
	v_mfma_f32_16x16x32_bf16 v[94:97], v[134:137], v[204:207], v[94:97]
	v_mfma_f32_16x16x32_bf16 v[78:81], v[130:133], v[208:211], v[78:81]
	v_mfma_f32_16x16x32_bf16 v[78:81], v[134:137], v[212:215], v[78:81]
	v_mfma_f32_16x16x32_bf16 v[122:125], v[138:141], v[174:177], v[122:125]
	v_mfma_f32_16x16x32_bf16 v[122:125], v[142:145], v[180:183], v[122:125]
	v_mfma_f32_16x16x32_bf16 v[106:109], v[138:141], v[184:187], v[106:109]
	v_mfma_f32_16x16x32_bf16 v[106:109], v[142:145], v[188:191], v[106:109]
	v_mfma_f32_16x16x32_bf16 v[90:93], v[138:141], v[200:203], v[90:93]
	v_mfma_f32_16x16x32_bf16 v[90:93], v[142:145], v[204:207], v[90:93]
	v_mfma_f32_16x16x32_bf16 v[74:77], v[138:141], v[208:211], v[74:77]
	v_mfma_f32_16x16x32_bf16 v[74:77], v[142:145], v[212:215], v[74:77]
	v_mfma_f32_16x16x32_bf16 v[118:121], v[146:149], v[174:177], v[118:121]
	v_mfma_f32_16x16x32_bf16 v[118:121], v[150:153], v[180:183], v[118:121]
	v_mfma_f32_16x16x32_bf16 v[102:105], v[146:149], v[184:187], v[102:105]
	v_mfma_f32_16x16x32_bf16 v[102:105], v[150:153], v[188:191], v[102:105]
	v_mfma_f32_16x16x32_bf16 v[86:89], v[146:149], v[200:203], v[86:89]
	v_mfma_f32_16x16x32_bf16 v[86:89], v[150:153], v[204:207], v[86:89]
	v_mfma_f32_16x16x32_bf16 v[70:73], v[146:149], v[208:211], v[70:73]
	v_mfma_f32_16x16x32_bf16 v[70:73], v[150:153], v[212:215], v[70:73]
	v_mfma_f32_16x16x32_bf16 v[114:117], v[154:157], v[174:177], v[114:117]
	v_mfma_f32_16x16x32_bf16 v[114:117], v[158:161], v[180:183], v[114:117]
	v_mfma_f32_16x16x32_bf16 v[98:101], v[154:157], v[184:187], v[98:101]
	v_mfma_f32_16x16x32_bf16 v[98:101], v[158:161], v[188:191], v[98:101]
	v_mfma_f32_16x16x32_bf16 v[82:85], v[154:157], v[200:203], v[82:85]
	v_mfma_f32_16x16x32_bf16 v[82:85], v[158:161], v[204:207], v[82:85]
	v_mfma_f32_16x16x32_bf16 v[66:69], v[154:157], v[208:211], v[66:69]
	v_mfma_f32_16x16x32_bf16 v[66:69], v[158:161], v[212:215], v[66:69]
	s_barrier
	s_add_i32 s30, s51, s9
	v_lshl_add_u64 v[194:195], v[194:195], 0, s[12:13]
	s_mov_b32 m0, s30
	ds_read_b128 v[174:177], v192 offset:49152
	ds_read_b128 v[180:183], v192 offset:50176
	ds_read_b128 v[184:187], v192 offset:51200
	ds_read_b128 v[188:191], v192 offset:52224
	ds_read_b128 v[200:203], v192 offset:53248
	ds_read_b128 v[204:207], v192 offset:54272
	ds_read_b128 v[208:211], v192 offset:55296
	ds_read_b128 v[212:215], v192 offset:56320
	global_load_lds_dwordx4 v[194:195], off
	s_add_i32 m0, s30, 0x2000
	s_add_u32 s28, s28, 0x100080
	v_lshl_add_u64 v[194:195], v[216:217], 0, s[12:13]
	s_addc_u32 s29, s29, 0
	s_add_i32 s30, s77, s9
	global_load_lds_dwordx4 v[194:195], off
	v_lshl_add_u64 v[194:195], s[28:29], 0, v[166:167]
	s_mov_b32 m0, s30
	s_nop 0
	global_load_lds_dwordx4 v[194:195], off
	v_lshl_add_u64 v[194:195], s[28:29], 0, v[162:163]
	s_add_i32 m0, s30, 0x2000
	s_nop 0
	global_load_lds_dwordx4 v[194:195], off
	v_lshl_add_u64 v[194:195], v[218:219], 0, s[12:13]
	s_mov_b32 m0, s54
	s_nop 0
	global_load_lds_dwordx4 v[194:195], off
	v_lshl_add_u64 v[194:195], v[220:221], 0, s[12:13]
	s_mov_b32 m0, s55
	s_nop 0
	global_load_lds_dwordx4 v[194:195], off
	s_waitcnt vmcnt(8)
	s_waitcnt lgkmcnt(0)
	s_barrier
	s_waitcnt lgkmcnt(0)
	v_mfma_f32_16x16x32_bf16 v[62:65], v[130:133], v[174:177], v[62:65]
	v_mfma_f32_16x16x32_bf16 v[62:65], v[134:137], v[180:183], v[62:65]
	v_mfma_f32_16x16x32_bf16 v[46:49], v[130:133], v[184:187], v[46:49]
	v_mfma_f32_16x16x32_bf16 v[46:49], v[134:137], v[188:191], v[46:49]
	v_mfma_f32_16x16x32_bf16 v[30:33], v[130:133], v[200:203], v[30:33]
	v_mfma_f32_16x16x32_bf16 v[30:33], v[134:137], v[204:207], v[30:33]
	v_mfma_f32_16x16x32_bf16 v[14:17], v[130:133], v[208:211], v[14:17]
	v_mfma_f32_16x16x32_bf16 v[14:17], v[134:137], v[212:215], v[14:17]
	v_mfma_f32_16x16x32_bf16 v[58:61], v[138:141], v[174:177], v[58:61]
	v_mfma_f32_16x16x32_bf16 v[58:61], v[142:145], v[180:183], v[58:61]
	v_mfma_f32_16x16x32_bf16 v[42:45], v[138:141], v[184:187], v[42:45]
	v_mfma_f32_16x16x32_bf16 v[42:45], v[142:145], v[188:191], v[42:45]
	v_mfma_f32_16x16x32_bf16 v[26:29], v[138:141], v[200:203], v[26:29]
	v_mfma_f32_16x16x32_bf16 v[26:29], v[142:145], v[204:207], v[26:29]
	v_mfma_f32_16x16x32_bf16 v[10:13], v[138:141], v[208:211], v[10:13]
	v_mfma_f32_16x16x32_bf16 v[10:13], v[142:145], v[212:215], v[10:13]
	v_mfma_f32_16x16x32_bf16 v[54:57], v[146:149], v[174:177], v[54:57]
	v_mfma_f32_16x16x32_bf16 v[54:57], v[150:153], v[180:183], v[54:57]
	v_mfma_f32_16x16x32_bf16 v[38:41], v[146:149], v[184:187], v[38:41]
	v_mfma_f32_16x16x32_bf16 v[38:41], v[150:153], v[188:191], v[38:41]
	v_mfma_f32_16x16x32_bf16 v[22:25], v[146:149], v[200:203], v[22:25]
	v_mfma_f32_16x16x32_bf16 v[22:25], v[150:153], v[204:207], v[22:25]
	v_mfma_f32_16x16x32_bf16 v[6:9], v[146:149], v[208:211], v[6:9]
	v_mfma_f32_16x16x32_bf16 v[6:9], v[150:153], v[212:215], v[6:9]
	v_mfma_f32_16x16x32_bf16 v[50:53], v[154:157], v[174:177], v[50:53]
	v_mfma_f32_16x16x32_bf16 v[50:53], v[158:161], v[180:183], v[50:53]
	v_mfma_f32_16x16x32_bf16 v[34:37], v[154:157], v[184:187], v[34:37]
	v_mfma_f32_16x16x32_bf16 v[34:37], v[158:161], v[188:191], v[34:37]
	v_mfma_f32_16x16x32_bf16 v[18:21], v[154:157], v[200:203], v[18:21]
	v_mfma_f32_16x16x32_bf16 v[18:21], v[158:161], v[204:207], v[18:21]
	v_mfma_f32_16x16x32_bf16 v[2:5], v[154:157], v[208:211], v[2:5]
	v_mfma_f32_16x16x32_bf16 v[2:5], v[158:161], v[212:215], v[2:5]
	s_barrier
	s_add_i32 s50, s50, 2
	s_add_u32 s0, s0, 0x100
	s_addc_u32 s1, s1, 0
	s_add_u32 s41, s41, 0x100
	s_addc_u32 s43, s43, 0
	s_cmp_gt_u32 s50, 61
	s_cbranch_scc0 .LBB0_230
	s_and_b64 vcc, exec, s[22:23]
	s_cbranch_vccz .LBB0_233
	s_barrier

.LBB0_300:
	s_add_u32 s100, s0, 0xfff80000
	s_addc_u32 s101, s1, -1
	s_add_u32 s28, s0, 0xfff80080
	s_addc_u32 s29, s1, -1
	s_add_i32 s42, 0, 0x10000
	s_cmp_eq_u32 s41, 28
	s_cselect_b32 s31, s18, s29
	s_cselect_b32 s30, s19, s28
	v_add_u32_e32 v0, s42, v199
	s_cselect_b32 s29, s27, s40
	s_cselect_b32 s28, s34, s35
	s_add_i32 s49, 0, 0x14000
	ds_read_b128 v[2:5], v0
	ds_read_b128 v[6:9], v0 offset:1024
	ds_read_b128 v[10:13], v0 offset:2048
	ds_read_b128 v[14:17], v0 offset:3072
	v_add_u32_e32 v0, s49, v199
	ds_read_b128 v[146:149], v0
	ds_read_b128 v[150:153], v0 offset:1024
	ds_read_b128 v[154:157], v0 offset:2048
	ds_read_b128 v[158:161], v0 offset:3072
	v_lshl_add_u64 v[194:195], s[100:101], 0, v[162:163]
	s_mov_b32 m0, s15
	ds_read_b128 v[174:177], v250
	ds_read_b128 v[178:181], v250 offset:1024
	ds_read_b128 v[182:185], v250 offset:2048
	ds_read_b128 v[186:189], v250 offset:3072
	ds_read_b128 v[190:193], v250 offset:4096
	ds_read_b128 v[200:203], v250 offset:5120
	ds_read_b128 v[204:207], v250 offset:6144
	ds_read_b128 v[208:211], v250 offset:7168
	global_load_lds_dwordx4 v[194:195], off
	v_lshl_add_u64 v[194:195], s[100:101], 0, v[166:167]
	s_mov_b32 m0, s88
	s_nop 0
	global_load_lds_dwordx4 v[194:195], off
	v_lshl_add_u64 v[194:195], s[0:1], 0, v[170:171]
	s_add_i32 m0, s21, 0xc000
	s_nop 0
	global_load_lds_dwordx4 v[194:195], off
	v_lshl_add_u64 v[194:195], s[0:1], 0, v[172:173]
	s_add_i32 m0, s21, 0xe000
	s_nop 0
	global_load_lds_dwordx4 v[194:195], off
	s_waitcnt vmcnt(8)
	s_waitcnt lgkmcnt(0)
	s_barrier
	s_waitcnt lgkmcnt(0)
	v_mfma_i32_16x16x64_i8 v[142:145], v[2:5], v[174:177], v[142:145]
	v_mfma_i32_16x16x64_i8 v[142:145], v[6:9], v[178:181], v[142:145]
	v_mfma_i32_16x16x64_i8 v[134:137], v[2:5], v[182:185], v[134:137]
	v_mfma_i32_16x16x64_i8 v[134:137], v[6:9], v[186:189], v[134:137]
	v_mfma_i32_16x16x64_i8 v[122:125], v[2:5], v[190:193], v[122:125]
	v_mfma_i32_16x16x64_i8 v[122:125], v[6:9], v[200:203], v[122:125]
	v_mfma_i32_16x16x64_i8 v[106:109], v[2:5], v[204:207], v[106:109]
	v_mfma_i32_16x16x64_i8 v[106:109], v[6:9], v[208:211], v[106:109]
	v_mfma_i32_16x16x64_i8 v[138:141], v[10:13], v[174:177], v[138:141]
	v_mfma_i32_16x16x64_i8 v[138:141], v[14:17], v[178:181], v[138:141]
	v_mfma_i32_16x16x64_i8 v[130:133], v[10:13], v[182:185], v[130:133]
	v_mfma_i32_16x16x64_i8 v[130:133], v[14:17], v[186:189], v[130:133]
	v_mfma_i32_16x16x64_i8 v[114:117], v[10:13], v[190:193], v[114:117]
	v_mfma_i32_16x16x64_i8 v[114:117], v[14:17], v[200:203], v[114:117]
	v_mfma_i32_16x16x64_i8 v[98:101], v[10:13], v[204:207], v[98:101]
	v_mfma_i32_16x16x64_i8 v[98:101], v[14:17], v[208:211], v[98:101]
	v_mfma_i32_16x16x64_i8 v[126:129], v[146:149], v[174:177], v[126:129]
	v_mfma_i32_16x16x64_i8 v[126:129], v[150:153], v[178:181], v[126:129]
	v_mfma_i32_16x16x64_i8 v[110:113], v[146:149], v[182:185], v[110:113]
	v_mfma_i32_16x16x64_i8 v[110:113], v[150:153], v[186:189], v[110:113]
	v_mfma_i32_16x16x64_i8 v[94:97], v[146:149], v[190:193], v[94:97]
	v_mfma_i32_16x16x64_i8 v[94:97], v[150:153], v[200:203], v[94:97]
	v_mfma_i32_16x16x64_i8 v[86:89], v[146:149], v[204:207], v[86:89]
	v_mfma_i32_16x16x64_i8 v[86:89], v[150:153], v[208:211], v[86:89]
	v_mfma_i32_16x16x64_i8 v[118:121], v[154:157], v[174:177], v[118:121]
	v_mfma_i32_16x16x64_i8 v[118:121], v[158:161], v[178:181], v[118:121]
	v_mfma_i32_16x16x64_i8 v[102:105], v[154:157], v[182:185], v[102:105]
	v_mfma_i32_16x16x64_i8 v[102:105], v[158:161], v[186:189], v[102:105]
	v_mfma_i32_16x16x64_i8 v[90:93], v[154:157], v[190:193], v[90:93]
	v_mfma_i32_16x16x64_i8 v[90:93], v[158:161], v[200:203], v[90:93]
	v_mfma_i32_16x16x64_i8 v[82:85], v[154:157], v[204:207], v[82:85]
	v_mfma_i32_16x16x64_i8 v[82:85], v[158:161], v[208:211], v[82:85]
	s_barrier
	s_add_i32 s42, s42, s81
	v_lshl_add_u64 v[194:195], s[28:29], 0, v[164:165]
	s_mov_b32 m0, s42
	ds_read_b128 v[174:177], v250 offset:16384
	ds_read_b128 v[178:181], v250 offset:17408
	ds_read_b128 v[182:185], v250 offset:18432
	ds_read_b128 v[186:189], v250 offset:19456
	ds_read_b128 v[190:193], v250 offset:20480
	ds_read_b128 v[200:203], v250 offset:21504
	ds_read_b128 v[204:207], v250 offset:22528
	ds_read_b128 v[208:211], v250 offset:23552
	global_load_lds_dwordx4 v[194:195], off
	s_add_i32 m0, s42, 0x2000
	s_add_u32 s42, s28, 0x80000
	v_lshl_add_u64 v[212:213], s[28:29], 0, v[168:169]
	s_addc_u32 s43, s29, 0
	s_add_i32 s49, s49, s81
	global_load_lds_dwordx4 v[212:213], off
	v_lshl_add_u64 v[214:215], s[42:43], 0, v[164:165]
	s_mov_b32 m0, s49
	v_lshl_add_u64 v[216:217], s[30:31], 0, v[166:167]
	global_load_lds_dwordx4 v[214:215], off
	v_lshl_add_u64 v[214:215], s[42:43], 0, v[168:169]
	s_add_i32 m0, s49, 0x2000
	s_nop 0
	global_load_lds_dwordx4 v[214:215], off
	v_lshl_add_u64 v[214:215], s[30:31], 0, v[162:163]
	s_waitcnt vmcnt(6)
	s_waitcnt lgkmcnt(0)
	s_barrier
	s_waitcnt lgkmcnt(0)
	v_mfma_i32_16x16x64_i8 v[78:81], v[2:5], v[174:177], v[78:81]
	v_mfma_i32_16x16x64_i8 v[78:81], v[6:9], v[178:181], v[78:81]
	v_mfma_i32_16x16x64_i8 v[74:77], v[10:13], v[174:177], v[74:77]
	v_mfma_i32_16x16x64_i8 v[74:77], v[14:17], v[178:181], v[74:77]
	v_mfma_i32_16x16x64_i8 v[70:73], v[2:5], v[182:185], v[70:73]
	v_mfma_i32_16x16x64_i8 v[70:73], v[6:9], v[186:189], v[70:73]
	v_mfma_i32_16x16x64_i8 v[66:69], v[10:13], v[182:185], v[66:69]
	v_mfma_i32_16x16x64_i8 v[66:69], v[14:17], v[186:189], v[66:69]
	v_mfma_i32_16x16x64_i8 v[54:57], v[2:5], v[190:193], v[54:57]
	v_mfma_i32_16x16x64_i8 v[54:57], v[6:9], v[200:203], v[54:57]
	v_mfma_i32_16x16x64_i8 v[50:53], v[10:13], v[190:193], v[50:53]
	v_mfma_i32_16x16x64_i8 v[50:53], v[14:17], v[200:203], v[50:53]
	v_mfma_i32_16x16x64_i8 v[2:5], v[2:5], v[204:207], v[38:41]
	v_mfma_i32_16x16x64_i8 v[2:5], v[6:9], v[208:211], v[2:5]
	v_mfma_i32_16x16x64_i8 v[6:9], v[10:13], v[204:207], v[34:37]
	v_mfma_i32_16x16x64_i8 v[6:9], v[14:17], v[208:211], v[6:9]
	v_mfma_i32_16x16x64_i8 v[34:37], v[146:149], v[182:185], v[46:49]
	v_mfma_i32_16x16x64_i8 v[46:49], v[150:153], v[186:189], v[34:37]
	v_mfma_i32_16x16x64_i8 v[34:37], v[154:157], v[182:185], v[42:45]
	v_mfma_i32_16x16x64_i8 v[42:45], v[158:161], v[186:189], v[34:37]
	v_mfma_i32_16x16x64_i8 v[30:33], v[146:149], v[190:193], v[30:33]
	v_mfma_i32_16x16x64_i8 v[30:33], v[150:153], v[200:203], v[30:33]
	v_mfma_i32_16x16x64_i8 v[26:29], v[154:157], v[190:193], v[26:29]
	v_mfma_i32_16x16x64_i8 v[26:29], v[158:161], v[200:203], v[26:29]
	v_mfma_i32_16x16x64_i8 v[22:25], v[146:149], v[204:207], v[22:25]
	v_mfma_i32_16x16x64_i8 v[22:25], v[150:153], v[208:211], v[22:25]
	v_mfma_i32_16x16x64_i8 v[18:21], v[154:157], v[204:207], v[18:21]
	v_mfma_i32_16x16x64_i8 v[18:21], v[158:161], v[208:211], v[18:21]
	v_mfma_i32_16x16x64_i8 v[10:13], v[146:149], v[174:177], v[62:65]
	v_mfma_i32_16x16x64_i8 v[10:13], v[150:153], v[178:181], v[10:13]
	v_mfma_i32_16x16x64_i8 v[14:17], v[154:157], v[174:177], v[58:61]
	v_mfma_i32_16x16x64_i8 v[14:17], v[158:161], v[178:181], v[14:17]
	s_barrier
	s_add_i32 s42, 0, 0x18000
	v_add_u32_e32 v0, s42, v199
	s_add_i32 s43, 0, 0x1c000
	ds_read_b128 v[34:37], v0
	ds_read_b128 v[38:41], v0 offset:1024
	ds_read_b128 v[58:61], v0 offset:2048
	ds_read_b128 v[62:65], v0 offset:3072
	v_add_u32_e32 v0, s43, v199
	ds_read_b128 v[146:149], v0
	ds_read_b128 v[150:153], v0 offset:1024
	ds_read_b128 v[154:157], v0 offset:2048
	ds_read_b128 v[158:161], v0 offset:3072
	s_add_u32 s30, s30, 0x80000
	s_addc_u32 s31, s31, 0
	s_mov_b32 m0, s21
	v_lshl_add_u64 v[218:219], s[30:31], 0, v[162:163]
	ds_read_b128 v[174:177], v250 offset:32768
	ds_read_b128 v[178:181], v250 offset:33792
	ds_read_b128 v[182:185], v250 offset:34816
	ds_read_b128 v[186:189], v250 offset:35840
	ds_read_b128 v[190:193], v250 offset:36864
	ds_read_b128 v[200:203], v250 offset:37888
	ds_read_b128 v[204:207], v250 offset:38912
	ds_read_b128 v[208:211], v250 offset:39936
	global_load_lds_dwordx4 v[214:215], off
	s_mov_b32 m0, s57
	s_nop 0
	global_load_lds_dwordx4 v[216:217], off
	s_mov_b32 m0, s73
	s_nop 0
	global_load_lds_dwordx4 v[218:219], off
	v_lshl_add_u64 v[218:219], s[30:31], 0, v[166:167]
	s_mov_b32 m0, s76
	s_nop 0
	global_load_lds_dwordx4 v[218:219], off
	s_waitcnt vmcnt(8)
	s_waitcnt lgkmcnt(0)
	s_barrier
	s_waitcnt lgkmcnt(0)
	v_mfma_i32_16x16x64_i8 v[142:145], v[34:37], v[174:177], v[142:145]
	v_mfma_i32_16x16x64_i8 v[142:145], v[38:41], v[178:181], v[142:145]
	v_mfma_i32_16x16x64_i8 v[134:137], v[34:37], v[182:185], v[134:137]
	v_mfma_i32_16x16x64_i8 v[134:137], v[38:41], v[186:189], v[134:137]
	v_mfma_i32_16x16x64_i8 v[122:125], v[34:37], v[190:193], v[122:125]
	v_mfma_i32_16x16x64_i8 v[122:125], v[38:41], v[200:203], v[122:125]
	v_mfma_i32_16x16x64_i8 v[106:109], v[34:37], v[204:207], v[106:109]
	v_mfma_i32_16x16x64_i8 v[106:109], v[38:41], v[208:211], v[106:109]
	v_mfma_i32_16x16x64_i8 v[138:141], v[58:61], v[174:177], v[138:141]
	v_mfma_i32_16x16x64_i8 v[138:141], v[62:65], v[178:181], v[138:141]
	v_mfma_i32_16x16x64_i8 v[130:133], v[58:61], v[182:185], v[130:133]
	v_mfma_i32_16x16x64_i8 v[130:133], v[62:65], v[186:189], v[130:133]
	v_mfma_i32_16x16x64_i8 v[114:117], v[58:61], v[190:193], v[114:117]
	v_mfma_i32_16x16x64_i8 v[114:117], v[62:65], v[200:203], v[114:117]
	v_mfma_i32_16x16x64_i8 v[98:101], v[58:61], v[204:207], v[98:101]
	v_mfma_i32_16x16x64_i8 v[98:101], v[62:65], v[208:211], v[98:101]
	v_mfma_i32_16x16x64_i8 v[126:129], v[146:149], v[174:177], v[126:129]
	v_mfma_i32_16x16x64_i8 v[126:129], v[150:153], v[178:181], v[126:129]
	v_mfma_i32_16x16x64_i8 v[110:113], v[146:149], v[182:185], v[110:113]
	v_mfma_i32_16x16x64_i8 v[110:113], v[150:153], v[186:189], v[110:113]
	v_mfma_i32_16x16x64_i8 v[94:97], v[146:149], v[190:193], v[94:97]
	v_mfma_i32_16x16x64_i8 v[94:97], v[150:153], v[200:203], v[94:97]
	v_mfma_i32_16x16x64_i8 v[86:89], v[146:149], v[204:207], v[86:89]
	v_mfma_i32_16x16x64_i8 v[86:89], v[150:153], v[208:211], v[86:89]
	v_mfma_i32_16x16x64_i8 v[118:121], v[154:157], v[174:177], v[118:121]
	v_mfma_i32_16x16x64_i8 v[118:121], v[158:161], v[178:181], v[118:121]
	v_mfma_i32_16x16x64_i8 v[102:105], v[154:157], v[182:185], v[102:105]
	v_mfma_i32_16x16x64_i8 v[102:105], v[158:161], v[186:189], v[102:105]
	v_mfma_i32_16x16x64_i8 v[90:93], v[154:157], v[190:193], v[90:93]
	v_mfma_i32_16x16x64_i8 v[90:93], v[158:161], v[200:203], v[90:93]
	v_mfma_i32_16x16x64_i8 v[82:85], v[154:157], v[204:207], v[82:85]
	v_mfma_i32_16x16x64_i8 v[82:85], v[158:161], v[208:211], v[82:85]
	s_barrier
	s_add_i32 s30, s42, s81
	v_lshl_add_u64 v[194:195], v[194:195], 0, s[12:13]
	s_mov_b32 m0, s30
	ds_read_b128 v[174:177], v250 offset:49152
	ds_read_b128 v[178:181], v250 offset:50176
	ds_read_b128 v[182:185], v250 offset:51200
	ds_read_b128 v[186:189], v250 offset:52224
	ds_read_b128 v[190:193], v250 offset:53248
	ds_read_b128 v[200:203], v250 offset:54272
	ds_read_b128 v[204:207], v250 offset:55296
	ds_read_b128 v[208:211], v250 offset:56320
	global_load_lds_dwordx4 v[194:195], off
	s_add_i32 m0, s30, 0x2000
	s_add_u32 s28, s28, 0x80080
	v_lshl_add_u64 v[194:195], v[212:213], 0, s[12:13]
	s_addc_u32 s29, s29, 0
	s_add_i32 s30, s43, s81
	global_load_lds_dwordx4 v[194:195], off
	v_lshl_add_u64 v[194:195], s[28:29], 0, v[164:165]
	s_mov_b32 m0, s30
	s_nop 0
	global_load_lds_dwordx4 v[194:195], off
	v_lshl_add_u64 v[194:195], s[28:29], 0, v[168:169]
	s_add_i32 m0, s30, 0x2000
	s_nop 0
	global_load_lds_dwordx4 v[194:195], off
	s_waitcnt vmcnt(6)
	s_waitcnt lgkmcnt(0)
	s_barrier
	s_waitcnt lgkmcnt(0)
	v_mfma_i32_16x16x64_i8 v[78:81], v[34:37], v[174:177], v[78:81]
	v_mfma_i32_16x16x64_i8 v[78:81], v[38:41], v[178:181], v[78:81]
	v_mfma_i32_16x16x64_i8 v[70:73], v[34:37], v[182:185], v[70:73]
	v_mfma_i32_16x16x64_i8 v[70:73], v[38:41], v[186:189], v[70:73]
	v_mfma_i32_16x16x64_i8 v[54:57], v[34:37], v[190:193], v[54:57]
	v_mfma_i32_16x16x64_i8 v[54:57], v[38:41], v[200:203], v[54:57]
	v_mfma_i32_16x16x64_i8 v[2:5], v[34:37], v[204:207], v[2:5]
	v_mfma_i32_16x16x64_i8 v[38:41], v[38:41], v[208:211], v[2:5]
	v_mfma_i32_16x16x64_i8 v[74:77], v[58:61], v[174:177], v[74:77]
	v_mfma_i32_16x16x64_i8 v[74:77], v[62:65], v[178:181], v[74:77]
	v_mfma_i32_16x16x64_i8 v[66:69], v[58:61], v[182:185], v[66:69]
	v_mfma_i32_16x16x64_i8 v[66:69], v[62:65], v[186:189], v[66:69]
	v_mfma_i32_16x16x64_i8 v[50:53], v[58:61], v[190:193], v[50:53]
	v_mfma_i32_16x16x64_i8 v[50:53], v[62:65], v[200:203], v[50:53]
	v_mfma_i32_16x16x64_i8 v[2:5], v[58:61], v[204:207], v[6:9]
	v_mfma_i32_16x16x64_i8 v[34:37], v[62:65], v[208:211], v[2:5]
	v_mfma_i32_16x16x64_i8 v[2:5], v[146:149], v[174:177], v[10:13]
	v_mfma_i32_16x16x64_i8 v[62:65], v[150:153], v[178:181], v[2:5]
	v_mfma_i32_16x16x64_i8 v[2:5], v[154:157], v[174:177], v[14:17]
	v_mfma_i32_16x16x64_i8 v[58:61], v[158:161], v[178:181], v[2:5]
	v_mfma_i32_16x16x64_i8 v[2:5], v[146:149], v[182:185], v[46:49]
	v_mfma_i32_16x16x64_i8 v[46:49], v[150:153], v[186:189], v[2:5]
	v_mfma_i32_16x16x64_i8 v[2:5], v[154:157], v[182:185], v[42:45]
	v_mfma_i32_16x16x64_i8 v[42:45], v[158:161], v[186:189], v[2:5]
	v_mfma_i32_16x16x64_i8 v[2:5], v[146:149], v[190:193], v[30:33]
	v_mfma_i32_16x16x64_i8 v[30:33], v[150:153], v[200:203], v[2:5]
	v_mfma_i32_16x16x64_i8 v[2:5], v[154:157], v[190:193], v[26:29]
	v_mfma_i32_16x16x64_i8 v[26:29], v[158:161], v[200:203], v[2:5]
	v_mfma_i32_16x16x64_i8 v[2:5], v[146:149], v[204:207], v[22:25]
	v_mfma_i32_16x16x64_i8 v[22:25], v[150:153], v[208:211], v[2:5]
	v_mfma_i32_16x16x64_i8 v[2:5], v[154:157], v[204:207], v[18:21]
	v_mfma_i32_16x16x64_i8 v[18:21], v[158:161], v[208:211], v[2:5]
	s_barrier
	s_add_i32 s41, s41, 2
	s_add_u32 s0, s0, 0x100
	s_addc_u32 s1, s1, 0
	s_add_u32 s35, s35, 0x100
	s_addc_u32 s40, s40, 0
	s_cmp_gt_u32 s41, 29
	s_cbranch_scc0 .LBB0_300
	s_and_b64 vcc, exec, s[52:53]
	s_cbranch_vccz .LBB0_303
	s_barrier

.LBB0_577:
	s_add_u32 s34, s30, 0xfff80080
	s_addc_u32 s35, s31, -1
	s_add_i32 s66, 0, 0x10000
	s_cmp_eq_u32 s57, 28
	s_cselect_b32 s43, s19, s35
	s_cselect_b32 s42, s23, s34
	v_add_u32_e32 v0, s66, v228
	s_cselect_b32 s35, s25, s56
	s_cselect_b32 s34, s54, s55
	s_add_i32 s73, 0, 0x14000
	ds_read_b128 v[132:135], v0
	ds_read_b128 v[136:139], v0 offset:1024
	ds_read_b128 v[140:143], v0 offset:2048
	ds_read_b128 v[144:147], v0 offset:3072
	v_add_u32_e32 v0, s73, v228
	ds_read_b128 v[148:151], v0
	ds_read_b128 v[152:155], v0 offset:1024
	ds_read_b128 v[156:159], v0 offset:2048
	ds_read_b128 v[160:163], v0 offset:3072
	v_lshl_add_u64 v[2:3], s[30:31], 0, v[208:209]
	s_add_i32 m0, s46, 0xc000
	ds_read_b128 v[164:167], v230
	ds_read_b128 v[168:171], v230 offset:1024
	ds_read_b128 v[172:175], v230 offset:2048
	ds_read_b128 v[176:179], v230 offset:3072
	ds_read_b128 v[180:183], v230 offset:4096
	ds_read_b128 v[184:187], v230 offset:5120
	ds_read_b128 v[188:191], v230 offset:6144
	ds_read_b128 v[192:195], v230 offset:7168
	global_load_lds_dwordx4 v[2:3], off
	v_lshl_add_u64 v[2:3], s[30:31], 0, v[210:211]
	s_add_i32 m0, s46, 0xe000
	s_nop 0
	global_load_lds_dwordx4 v[2:3], off
	s_waitcnt vmcnt(8)
	s_waitcnt lgkmcnt(0)
	s_barrier
	s_waitcnt lgkmcnt(0)
	v_mfma_f32_16x16x32_bf16 v[128:131], v[132:135], v[164:167], v[128:131]
	v_mfma_f32_16x16x32_bf16 v[128:131], v[136:139], v[168:171], v[128:131]
	v_mfma_f32_16x16x32_bf16 v[120:123], v[132:135], v[172:175], v[120:123]
	v_mfma_f32_16x16x32_bf16 v[120:123], v[136:139], v[176:179], v[120:123]
	v_mfma_f32_16x16x32_bf16 v[112:115], v[132:135], v[180:183], v[112:115]
	v_mfma_f32_16x16x32_bf16 v[112:115], v[136:139], v[184:187], v[112:115]
	v_mfma_f32_16x16x32_bf16 v[104:107], v[132:135], v[188:191], v[104:107]
	v_mfma_f32_16x16x32_bf16 v[104:107], v[136:139], v[192:195], v[104:107]
	v_mfma_f32_16x16x32_bf16 v[124:127], v[140:143], v[164:167], v[124:127]
	v_mfma_f32_16x16x32_bf16 v[124:127], v[144:147], v[168:171], v[124:127]
	v_mfma_f32_16x16x32_bf16 v[116:119], v[140:143], v[172:175], v[116:119]
	v_mfma_f32_16x16x32_bf16 v[116:119], v[144:147], v[176:179], v[116:119]
	v_mfma_f32_16x16x32_bf16 v[108:111], v[140:143], v[180:183], v[108:111]
	v_mfma_f32_16x16x32_bf16 v[108:111], v[144:147], v[184:187], v[108:111]
	v_mfma_f32_16x16x32_bf16 v[100:103], v[140:143], v[188:191], v[100:103]
	v_mfma_f32_16x16x32_bf16 v[100:103], v[144:147], v[192:195], v[100:103]
	v_mfma_f32_16x16x32_bf16 v[96:99], v[148:151], v[164:167], v[96:99]
	v_mfma_f32_16x16x32_bf16 v[96:99], v[152:155], v[168:171], v[96:99]
	v_mfma_f32_16x16x32_bf16 v[88:91], v[148:151], v[172:175], v[88:91]
	v_mfma_f32_16x16x32_bf16 v[88:91], v[152:155], v[176:179], v[88:91]
	v_mfma_f32_16x16x32_bf16 v[80:83], v[148:151], v[180:183], v[80:83]
	v_mfma_f32_16x16x32_bf16 v[80:83], v[152:155], v[184:187], v[80:83]
	v_mfma_f32_16x16x32_bf16 v[72:75], v[148:151], v[188:191], v[72:75]
	v_mfma_f32_16x16x32_bf16 v[72:75], v[152:155], v[192:195], v[72:75]
	v_mfma_f32_16x16x32_bf16 v[92:95], v[156:159], v[164:167], v[92:95]
	v_mfma_f32_16x16x32_bf16 v[92:95], v[160:163], v[168:171], v[92:95]
	v_mfma_f32_16x16x32_bf16 v[84:87], v[156:159], v[172:175], v[84:87]
	v_mfma_f32_16x16x32_bf16 v[84:87], v[160:163], v[176:179], v[84:87]
	v_mfma_f32_16x16x32_bf16 v[76:79], v[156:159], v[180:183], v[76:79]
	v_mfma_f32_16x16x32_bf16 v[76:79], v[160:163], v[184:187], v[76:79]
	v_mfma_f32_16x16x32_bf16 v[68:71], v[156:159], v[188:191], v[68:71]
	v_mfma_f32_16x16x32_bf16 v[68:71], v[160:163], v[192:195], v[68:71]
	s_barrier
	s_add_i32 s66, s66, s15
	v_lshl_add_u64 v[212:213], s[34:35], 0, v[204:205]
	s_mov_b32 m0, s66
	ds_read_b128 v[164:167], v230 offset:16384
	ds_read_b128 v[168:171], v230 offset:17408
	ds_read_b128 v[172:175], v230 offset:18432
	ds_read_b128 v[176:179], v230 offset:19456
	ds_read_b128 v[180:183], v230 offset:20480
	ds_read_b128 v[184:187], v230 offset:21504
	ds_read_b128 v[188:191], v230 offset:22528
	ds_read_b128 v[192:195], v230 offset:23552
	global_load_lds_dwordx4 v[212:213], off
	s_add_i32 m0, s66, 0x2000
	s_add_u32 s66, s34, 0x80000
	v_lshl_add_u64 v[214:215], s[34:35], 0, v[200:201]
	s_addc_u32 s67, s35, 0
	s_add_i32 s73, s73, s15
	global_load_lds_dwordx4 v[214:215], off
	v_lshl_add_u64 v[2:3], s[66:67], 0, v[204:205]
	s_mov_b32 m0, s73
	v_lshl_add_u64 v[216:217], s[42:43], 0, v[206:207]
	global_load_lds_dwordx4 v[2:3], off
	v_lshl_add_u64 v[2:3], s[66:67], 0, v[200:201]
	s_add_i32 m0, s73, 0x2000
	v_lshl_add_u64 v[218:219], s[42:43], 0, v[202:203]
	global_load_lds_dwordx4 v[2:3], off
	s_mov_b32 m0, s46
	s_nop 0
	global_load_lds_dwordx4 v[216:217], off
	s_mov_b32 m0, s47
	s_nop 0
	global_load_lds_dwordx4 v[218:219], off
	s_waitcnt vmcnt(8)
	s_waitcnt lgkmcnt(0)
	s_barrier
	s_waitcnt lgkmcnt(0)
	v_mfma_f32_16x16x32_bf16 v[64:67], v[132:135], v[164:167], v[64:67]
	v_mfma_f32_16x16x32_bf16 v[64:67], v[136:139], v[168:171], v[64:67]
	v_mfma_f32_16x16x32_bf16 v[56:59], v[132:135], v[172:175], v[56:59]
	v_mfma_f32_16x16x32_bf16 v[56:59], v[136:139], v[176:179], v[56:59]
	v_mfma_f32_16x16x32_bf16 v[48:51], v[132:135], v[180:183], v[48:51]
	v_mfma_f32_16x16x32_bf16 v[48:51], v[136:139], v[184:187], v[48:51]
	v_mfma_f32_16x16x32_bf16 v[40:43], v[132:135], v[188:191], v[40:43]
	v_mfma_f32_16x16x32_bf16 v[40:43], v[136:139], v[192:195], v[40:43]
	v_mfma_f32_16x16x32_bf16 v[60:63], v[140:143], v[164:167], v[60:63]
	v_mfma_f32_16x16x32_bf16 v[60:63], v[144:147], v[168:171], v[60:63]
	v_mfma_f32_16x16x32_bf16 v[52:55], v[140:143], v[172:175], v[52:55]
	v_mfma_f32_16x16x32_bf16 v[52:55], v[144:147], v[176:179], v[52:55]
	v_mfma_f32_16x16x32_bf16 v[44:47], v[140:143], v[180:183], v[44:47]
	v_mfma_f32_16x16x32_bf16 v[44:47], v[144:147], v[184:187], v[44:47]
	v_mfma_f32_16x16x32_bf16 v[36:39], v[140:143], v[188:191], v[36:39]
	v_mfma_f32_16x16x32_bf16 v[36:39], v[144:147], v[192:195], v[36:39]
	v_mfma_f32_16x16x32_bf16 v[32:35], v[148:151], v[164:167], v[32:35]
	v_mfma_f32_16x16x32_bf16 v[32:35], v[152:155], v[168:171], v[32:35]
	v_mfma_f32_16x16x32_bf16 v[28:31], v[156:159], v[164:167], v[28:31]
	v_mfma_f32_16x16x32_bf16 v[28:31], v[160:163], v[168:171], v[28:31]
	v_mfma_f32_16x16x32_bf16 v[24:27], v[148:151], v[172:175], v[24:27]
	v_mfma_f32_16x16x32_bf16 v[24:27], v[152:155], v[176:179], v[24:27]
	v_mfma_f32_16x16x32_bf16 v[20:23], v[156:159], v[172:175], v[20:23]
	v_mfma_f32_16x16x32_bf16 v[20:23], v[160:163], v[176:179], v[20:23]
	v_mfma_f32_16x16x32_bf16 v[16:19], v[148:151], v[180:183], v[16:19]
	v_mfma_f32_16x16x32_bf16 v[16:19], v[152:155], v[184:187], v[16:19]
	v_mfma_f32_16x16x32_bf16 v[12:15], v[156:159], v[180:183], v[12:15]
	v_mfma_f32_16x16x32_bf16 v[12:15], v[160:163], v[184:187], v[12:15]
	v_mfma_f32_16x16x32_bf16 v[8:11], v[148:151], v[188:191], v[8:11]
	v_mfma_f32_16x16x32_bf16 v[8:11], v[152:155], v[192:195], v[8:11]
	v_mfma_f32_16x16x32_bf16 v[2:5], v[156:159], v[188:191], v[4:7]
	v_mfma_f32_16x16x32_bf16 v[2:5], v[160:163], v[192:195], v[2:5]
	s_barrier
	s_add_i32 s66, 0, 0x18000
	v_add_u32_e32 v0, s66, v228
	s_add_i32 s67, 0, 0x1c000
	ds_read_b128 v[132:135], v0
	ds_read_b128 v[136:139], v0 offset:1024
	ds_read_b128 v[140:143], v0 offset:2048
	ds_read_b128 v[144:147], v0 offset:3072
	v_add_u32_e32 v0, s67, v228
	ds_read_b128 v[148:151], v0
	ds_read_b128 v[152:155], v0 offset:1024
	ds_read_b128 v[156:159], v0 offset:2048
	ds_read_b128 v[160:163], v0 offset:3072
	s_add_u32 s42, s42, 0x80000
	s_addc_u32 s43, s43, 0
	s_mov_b32 m0, s48
	v_lshl_add_u64 v[6:7], s[42:43], 0, v[206:207]
	ds_read_b128 v[164:167], v230 offset:32768
	ds_read_b128 v[168:171], v230 offset:33792
	ds_read_b128 v[172:175], v230 offset:34816
	ds_read_b128 v[176:179], v230 offset:35840
	ds_read_b128 v[180:183], v230 offset:36864
	ds_read_b128 v[184:187], v230 offset:37888
	ds_read_b128 v[188:191], v230 offset:38912
	ds_read_b128 v[192:195], v230 offset:39936
	global_load_lds_dwordx4 v[6:7], off
	v_lshl_add_u64 v[6:7], s[42:43], 0, v[202:203]
	s_mov_b32 m0, s49
	s_nop 0
	global_load_lds_dwordx4 v[6:7], off
	s_waitcnt vmcnt(8)
	s_waitcnt lgkmcnt(0)
	s_barrier
	s_waitcnt lgkmcnt(0)
	v_mfma_f32_16x16x32_bf16 v[128:131], v[132:135], v[164:167], v[128:131]
	v_mfma_f32_16x16x32_bf16 v[128:131], v[136:139], v[168:171], v[128:131]
	v_mfma_f32_16x16x32_bf16 v[120:123], v[132:135], v[172:175], v[120:123]
	v_mfma_f32_16x16x32_bf16 v[120:123], v[136:139], v[176:179], v[120:123]
	v_mfma_f32_16x16x32_bf16 v[112:115], v[132:135], v[180:183], v[112:115]
	v_mfma_f32_16x16x32_bf16 v[112:115], v[136:139], v[184:187], v[112:115]
	v_mfma_f32_16x16x32_bf16 v[104:107], v[132:135], v[188:191], v[104:107]
	v_mfma_f32_16x16x32_bf16 v[104:107], v[136:139], v[192:195], v[104:107]
	v_mfma_f32_16x16x32_bf16 v[124:127], v[140:143], v[164:167], v[124:127]
	v_mfma_f32_16x16x32_bf16 v[124:127], v[144:147], v[168:171], v[124:127]
	v_mfma_f32_16x16x32_bf16 v[116:119], v[140:143], v[172:175], v[116:119]
	v_mfma_f32_16x16x32_bf16 v[116:119], v[144:147], v[176:179], v[116:119]
	v_mfma_f32_16x16x32_bf16 v[108:111], v[140:143], v[180:183], v[108:111]
	v_mfma_f32_16x16x32_bf16 v[108:111], v[144:147], v[184:187], v[108:111]
	v_mfma_f32_16x16x32_bf16 v[100:103], v[140:143], v[188:191], v[100:103]
	v_mfma_f32_16x16x32_bf16 v[100:103], v[144:147], v[192:195], v[100:103]
	v_mfma_f32_16x16x32_bf16 v[96:99], v[148:151], v[164:167], v[96:99]
	v_mfma_f32_16x16x32_bf16 v[96:99], v[152:155], v[168:171], v[96:99]
	v_mfma_f32_16x16x32_bf16 v[88:91], v[148:151], v[172:175], v[88:91]
	v_mfma_f32_16x16x32_bf16 v[88:91], v[152:155], v[176:179], v[88:91]
	v_mfma_f32_16x16x32_bf16 v[80:83], v[148:151], v[180:183], v[80:83]
	v_mfma_f32_16x16x32_bf16 v[80:83], v[152:155], v[184:187], v[80:83]
	v_mfma_f32_16x16x32_bf16 v[72:75], v[148:151], v[188:191], v[72:75]
	v_mfma_f32_16x16x32_bf16 v[72:75], v[152:155], v[192:195], v[72:75]
	v_mfma_f32_16x16x32_bf16 v[92:95], v[156:159], v[164:167], v[92:95]
	v_mfma_f32_16x16x32_bf16 v[92:95], v[160:163], v[168:171], v[92:95]
	v_mfma_f32_16x16x32_bf16 v[84:87], v[156:159], v[172:175], v[84:87]
	v_mfma_f32_16x16x32_bf16 v[84:87], v[160:163], v[176:179], v[84:87]
	v_mfma_f32_16x16x32_bf16 v[76:79], v[156:159], v[180:183], v[76:79]
	v_mfma_f32_16x16x32_bf16 v[76:79], v[160:163], v[184:187], v[76:79]
	v_mfma_f32_16x16x32_bf16 v[68:71], v[156:159], v[188:191], v[68:71]
	v_mfma_f32_16x16x32_bf16 v[68:71], v[160:163], v[192:195], v[68:71]
	s_barrier
	s_add_i32 s42, s66, s15
	v_lshl_add_u64 v[6:7], v[212:213], 0, s[12:13]
	s_mov_b32 m0, s42
	ds_read_b128 v[164:167], v230 offset:49152
	ds_read_b128 v[168:171], v230 offset:50176
	ds_read_b128 v[172:175], v230 offset:51200
	ds_read_b128 v[176:179], v230 offset:52224
	ds_read_b128 v[180:183], v230 offset:53248
	ds_read_b128 v[184:187], v230 offset:54272
	ds_read_b128 v[188:191], v230 offset:55296
	ds_read_b128 v[192:195], v230 offset:56320
	global_load_lds_dwordx4 v[6:7], off
	s_add_i32 m0, s42, 0x2000
	s_add_u32 s34, s34, 0x80080
	v_lshl_add_u64 v[6:7], v[214:215], 0, s[12:13]
	s_addc_u32 s35, s35, 0
	s_add_i32 s42, s67, s15
	global_load_lds_dwordx4 v[6:7], off
	v_lshl_add_u64 v[6:7], s[34:35], 0, v[204:205]
	s_mov_b32 m0, s42
	s_nop 0
	global_load_lds_dwordx4 v[6:7], off
	v_lshl_add_u64 v[6:7], s[34:35], 0, v[200:201]
	s_add_i32 m0, s42, 0x2000
	s_nop 0
	global_load_lds_dwordx4 v[6:7], off
	v_lshl_add_u64 v[6:7], v[216:217], 0, s[12:13]
	s_mov_b32 m0, s50
	s_nop 0
	global_load_lds_dwordx4 v[6:7], off
	v_lshl_add_u64 v[6:7], v[218:219], 0, s[12:13]
	s_mov_b32 m0, s51
	s_nop 0
	global_load_lds_dwordx4 v[6:7], off
	s_waitcnt vmcnt(8)
	s_waitcnt lgkmcnt(0)
	s_barrier
	s_waitcnt lgkmcnt(0)
	v_mfma_f32_16x16x32_bf16 v[64:67], v[132:135], v[164:167], v[64:67]
	v_mfma_f32_16x16x32_bf16 v[64:67], v[136:139], v[168:171], v[64:67]
	v_mfma_f32_16x16x32_bf16 v[56:59], v[132:135], v[172:175], v[56:59]
	v_mfma_f32_16x16x32_bf16 v[56:59], v[136:139], v[176:179], v[56:59]
	v_mfma_f32_16x16x32_bf16 v[48:51], v[132:135], v[180:183], v[48:51]
	v_mfma_f32_16x16x32_bf16 v[48:51], v[136:139], v[184:187], v[48:51]
	v_mfma_f32_16x16x32_bf16 v[40:43], v[132:135], v[188:191], v[40:43]
	v_mfma_f32_16x16x32_bf16 v[40:43], v[136:139], v[192:195], v[40:43]
	v_mfma_f32_16x16x32_bf16 v[60:63], v[140:143], v[164:167], v[60:63]
	v_mfma_f32_16x16x32_bf16 v[60:63], v[144:147], v[168:171], v[60:63]
	v_mfma_f32_16x16x32_bf16 v[52:55], v[140:143], v[172:175], v[52:55]
	v_mfma_f32_16x16x32_bf16 v[52:55], v[144:147], v[176:179], v[52:55]
	v_mfma_f32_16x16x32_bf16 v[44:47], v[140:143], v[180:183], v[44:47]
	v_mfma_f32_16x16x32_bf16 v[44:47], v[144:147], v[184:187], v[44:47]
	v_mfma_f32_16x16x32_bf16 v[36:39], v[140:143], v[188:191], v[36:39]
	v_mfma_f32_16x16x32_bf16 v[36:39], v[144:147], v[192:195], v[36:39]
	v_mfma_f32_16x16x32_bf16 v[32:35], v[148:151], v[164:167], v[32:35]
	v_mfma_f32_16x16x32_bf16 v[32:35], v[152:155], v[168:171], v[32:35]
	v_mfma_f32_16x16x32_bf16 v[28:31], v[156:159], v[164:167], v[28:31]
	v_mfma_f32_16x16x32_bf16 v[28:31], v[160:163], v[168:171], v[28:31]
	v_mfma_f32_16x16x32_bf16 v[24:27], v[148:151], v[172:175], v[24:27]
	v_mfma_f32_16x16x32_bf16 v[24:27], v[152:155], v[176:179], v[24:27]
	v_mfma_f32_16x16x32_bf16 v[20:23], v[156:159], v[172:175], v[20:23]
	v_mfma_f32_16x16x32_bf16 v[20:23], v[160:163], v[176:179], v[20:23]
	v_mfma_f32_16x16x32_bf16 v[16:19], v[148:151], v[180:183], v[16:19]
	v_mfma_f32_16x16x32_bf16 v[16:19], v[152:155], v[184:187], v[16:19]
	v_mfma_f32_16x16x32_bf16 v[12:15], v[156:159], v[180:183], v[12:15]
	v_mfma_f32_16x16x32_bf16 v[12:15], v[160:163], v[184:187], v[12:15]
	v_mfma_f32_16x16x32_bf16 v[6:9], v[148:151], v[188:191], v[8:11]
	v_mfma_f32_16x16x32_bf16 v[8:11], v[152:155], v[192:195], v[6:9]
	v_mfma_f32_16x16x32_bf16 v[2:5], v[156:159], v[188:191], v[2:5]
	v_mfma_f32_16x16x32_bf16 v[4:7], v[160:163], v[192:195], v[2:5]
	s_barrier
	s_add_i32 s57, s57, 2
	s_add_u32 s30, s30, 0x100
	s_addc_u32 s31, s31, 0
	s_add_u32 s55, s55, 0x100
	s_addc_u32 s56, s56, 0
	s_cmp_gt_u32 s57, 29
	s_cbranch_scc0 .LBB0_577
	s_and_b64 vcc, exec, s[20:21]
	s_cbranch_vccz .LBB0_580
	s_barrier

.LBB0_779:
	s_add_u32 s34, s30, 0xfff80080
	s_addc_u32 s35, s31, -1
	s_add_i32 s66, 0, 0x10000
	s_cmp_eq_u32 s57, 28
	s_cselect_b32 s43, s25, s35
	s_cselect_b32 s42, s53, s34
	s_cselect_b32 s35, s23, s56
	s_cselect_b32 s34, s54, s55
	s_add_i32 s73, 0, 0x14000
	v_add_u32_e32 v114, s66, v157
	v_add_u32_e32 v156, s73, v157
	ds_read_b128 v[90:93], v114
	ds_read_b128 v[94:97], v114 offset:1024
	ds_read_b128 v[106:109], v114 offset:2048
	ds_read_b128 v[114:117], v114 offset:3072
	ds_read_b128 v[162:165], v156
	ds_read_b128 v[166:169], v156 offset:1024
	ds_read_b128 v[170:173], v156 offset:2048
	ds_read_b128 v[174:177], v156 offset:3072
	v_lshl_add_u64 v[158:159], s[30:31], 0, v[152:153]
	s_add_i32 m0, s14, 0xc000
	ds_read_b128 v[178:181], v161
	ds_read_b128 v[182:185], v161 offset:1024
	ds_read_b128 v[186:189], v161 offset:2048
	ds_read_b128 v[190:193], v161 offset:3072
	ds_read_b128 v[200:203], v161 offset:4096
	ds_read_b128 v[204:207], v161 offset:5120
	ds_read_b128 v[208:211], v161 offset:6144
	ds_read_b128 v[212:215], v161 offset:7168
	global_load_lds_dwordx4 v[158:159], off
	v_lshl_add_u64 v[158:159], s[30:31], 0, v[154:155]
	s_add_i32 m0, s14, 0xe000
	s_nop 0
	global_load_lds_dwordx4 v[158:159], off
	s_waitcnt vmcnt(8)
	s_waitcnt lgkmcnt(0)
	s_barrier
	s_waitcnt lgkmcnt(0)
	v_mfma_i32_16x16x64_i8 v[142:145], v[90:93], v[178:181], v[142:145]
	v_mfma_i32_16x16x64_i8 v[142:145], v[94:97], v[182:185], v[142:145]
	v_mfma_i32_16x16x64_i8 v[126:129], v[90:93], v[186:189], v[126:129]
	v_mfma_i32_16x16x64_i8 v[126:129], v[94:97], v[190:193], v[126:129]
	v_mfma_i32_16x16x64_i8 v[102:105], v[90:93], v[200:203], v[102:105]
	v_mfma_i32_16x16x64_i8 v[102:105], v[94:97], v[204:207], v[102:105]
	v_mfma_i32_16x16x64_i8 v[78:81], v[90:93], v[208:211], v[78:81]
	v_mfma_i32_16x16x64_i8 v[78:81], v[94:97], v[212:215], v[78:81]
	v_mfma_i32_16x16x64_i8 v[138:141], v[106:109], v[178:181], v[138:141]
	v_mfma_i32_16x16x64_i8 v[138:141], v[114:117], v[182:185], v[138:141]
	v_mfma_i32_16x16x64_i8 v[122:125], v[106:109], v[186:189], v[122:125]
	v_mfma_i32_16x16x64_i8 v[122:125], v[114:117], v[190:193], v[122:125]
	v_mfma_i32_16x16x64_i8 v[98:101], v[106:109], v[200:203], v[98:101]
	v_mfma_i32_16x16x64_i8 v[98:101], v[114:117], v[204:207], v[98:101]
	v_mfma_i32_16x16x64_i8 v[74:77], v[106:109], v[208:211], v[74:77]
	v_mfma_i32_16x16x64_i8 v[74:77], v[114:117], v[212:215], v[74:77]
	v_mfma_i32_16x16x64_i8 v[134:137], v[162:165], v[178:181], v[134:137]
	v_mfma_i32_16x16x64_i8 v[134:137], v[166:169], v[182:185], v[134:137]
	v_mfma_i32_16x16x64_i8 v[118:121], v[162:165], v[186:189], v[118:121]
	v_mfma_i32_16x16x64_i8 v[118:121], v[166:169], v[190:193], v[118:121]
	v_mfma_i32_16x16x64_i8 v[86:89], v[162:165], v[200:203], v[86:89]
	v_mfma_i32_16x16x64_i8 v[86:89], v[166:169], v[204:207], v[86:89]
	v_mfma_i32_16x16x64_i8 v[70:73], v[162:165], v[208:211], v[70:73]
	v_mfma_i32_16x16x64_i8 v[70:73], v[166:169], v[212:215], v[70:73]
	v_mfma_i32_16x16x64_i8 v[130:133], v[170:173], v[178:181], v[130:133]
	v_mfma_i32_16x16x64_i8 v[130:133], v[174:177], v[182:185], v[130:133]
	v_mfma_i32_16x16x64_i8 v[110:113], v[170:173], v[186:189], v[110:113]
	v_mfma_i32_16x16x64_i8 v[110:113], v[174:177], v[190:193], v[110:113]
	v_mfma_i32_16x16x64_i8 v[82:85], v[170:173], v[200:203], v[82:85]
	v_mfma_i32_16x16x64_i8 v[82:85], v[174:177], v[204:207], v[82:85]
	v_mfma_i32_16x16x64_i8 v[66:69], v[170:173], v[208:211], v[66:69]
	v_mfma_i32_16x16x64_i8 v[66:69], v[174:177], v[212:215], v[66:69]
	s_barrier
	s_add_i32 s66, s66, s9
	v_lshl_add_u64 v[158:159], s[34:35], 0, v[0:1]
	s_mov_b32 m0, s66
	ds_read_b128 v[178:181], v161 offset:16384
	ds_read_b128 v[182:185], v161 offset:17408
	ds_read_b128 v[186:189], v161 offset:18432
	ds_read_b128 v[190:193], v161 offset:19456
	ds_read_b128 v[200:203], v161 offset:20480
	ds_read_b128 v[204:207], v161 offset:21504
	ds_read_b128 v[208:211], v161 offset:22528
	ds_read_b128 v[212:215], v161 offset:23552
	global_load_lds_dwordx4 v[158:159], off
	s_add_i32 m0, s66, 0x2000
	s_add_u32 s66, s34, 0x80000
	v_lshl_add_u64 v[194:195], s[34:35], 0, v[146:147]
	s_addc_u32 s67, s35, 0
	s_add_i32 s73, s73, s9
	global_load_lds_dwordx4 v[194:195], off
	v_lshl_add_u64 v[216:217], s[66:67], 0, v[0:1]
	s_mov_b32 m0, s73
	v_lshl_add_u64 v[218:219], s[42:43], 0, v[148:149]
	global_load_lds_dwordx4 v[216:217], off
	v_lshl_add_u64 v[216:217], s[66:67], 0, v[146:147]
	s_add_i32 m0, s73, 0x2000
	s_nop 0
	global_load_lds_dwordx4 v[216:217], off
	v_lshl_add_u64 v[216:217], s[42:43], 0, v[150:151]
	s_mov_b32 m0, s14
	s_nop 0
	global_load_lds_dwordx4 v[216:217], off
	s_mov_b32 m0, s15
	s_nop 0
	global_load_lds_dwordx4 v[218:219], off
	s_waitcnt vmcnt(8)
	s_waitcnt lgkmcnt(0)
	s_barrier
	s_waitcnt lgkmcnt(0)
	v_mfma_i32_16x16x64_i8 v[62:65], v[90:93], v[178:181], v[62:65]
	v_mfma_i32_16x16x64_i8 v[62:65], v[94:97], v[182:185], v[62:65]
	v_mfma_i32_16x16x64_i8 v[46:49], v[90:93], v[186:189], v[46:49]
	v_mfma_i32_16x16x64_i8 v[46:49], v[94:97], v[190:193], v[46:49]
	v_mfma_i32_16x16x64_i8 v[30:33], v[90:93], v[200:203], v[30:33]
	v_mfma_i32_16x16x64_i8 v[30:33], v[94:97], v[204:207], v[30:33]
	v_mfma_i32_16x16x64_i8 v[14:17], v[90:93], v[208:211], v[14:17]
	v_mfma_i32_16x16x64_i8 v[14:17], v[94:97], v[212:215], v[14:17]
	v_mfma_i32_16x16x64_i8 v[58:61], v[106:109], v[178:181], v[58:61]
	v_mfma_i32_16x16x64_i8 v[58:61], v[114:117], v[182:185], v[58:61]
	v_mfma_i32_16x16x64_i8 v[42:45], v[106:109], v[186:189], v[42:45]
	v_mfma_i32_16x16x64_i8 v[42:45], v[114:117], v[190:193], v[42:45]
	v_mfma_i32_16x16x64_i8 v[26:29], v[106:109], v[200:203], v[26:29]
	v_mfma_i32_16x16x64_i8 v[26:29], v[114:117], v[204:207], v[26:29]
	v_mfma_i32_16x16x64_i8 v[10:13], v[106:109], v[208:211], v[10:13]
	v_mfma_i32_16x16x64_i8 v[10:13], v[114:117], v[212:215], v[10:13]
	v_mfma_i32_16x16x64_i8 v[54:57], v[162:165], v[178:181], v[54:57]
	v_mfma_i32_16x16x64_i8 v[54:57], v[166:169], v[182:185], v[54:57]
	v_mfma_i32_16x16x64_i8 v[38:41], v[162:165], v[186:189], v[38:41]
	v_mfma_i32_16x16x64_i8 v[38:41], v[166:169], v[190:193], v[38:41]
	v_mfma_i32_16x16x64_i8 v[22:25], v[162:165], v[200:203], v[22:25]
	v_mfma_i32_16x16x64_i8 v[22:25], v[166:169], v[204:207], v[22:25]
	v_mfma_i32_16x16x64_i8 v[6:9], v[162:165], v[208:211], v[6:9]
	v_mfma_i32_16x16x64_i8 v[6:9], v[166:169], v[212:215], v[6:9]
	v_mfma_i32_16x16x64_i8 v[50:53], v[170:173], v[178:181], v[50:53]
	v_mfma_i32_16x16x64_i8 v[50:53], v[174:177], v[182:185], v[50:53]
	v_mfma_i32_16x16x64_i8 v[34:37], v[170:173], v[186:189], v[34:37]
	v_mfma_i32_16x16x64_i8 v[34:37], v[174:177], v[190:193], v[34:37]
	v_mfma_i32_16x16x64_i8 v[18:21], v[170:173], v[200:203], v[18:21]
	v_mfma_i32_16x16x64_i8 v[18:21], v[174:177], v[204:207], v[18:21]
	v_mfma_i32_16x16x64_i8 v[2:5], v[170:173], v[208:211], v[2:5]
	v_mfma_i32_16x16x64_i8 v[2:5], v[174:177], v[212:215], v[2:5]
	s_barrier
	s_add_i32 s66, 0, 0x18000
	s_add_i32 s67, 0, 0x1c000
	v_add_u32_e32 v114, s66, v157
	v_add_u32_e32 v156, s67, v157
	ds_read_b128 v[90:93], v114
	ds_read_b128 v[94:97], v114 offset:1024
	ds_read_b128 v[106:109], v114 offset:2048
	ds_read_b128 v[114:117], v114 offset:3072
	ds_read_b128 v[162:165], v156
	ds_read_b128 v[166:169], v156 offset:1024
	ds_read_b128 v[170:173], v156 offset:2048
	ds_read_b128 v[174:177], v156 offset:3072
	s_add_u32 s42, s42, 0x80000
	s_addc_u32 s43, s43, 0
	s_mov_b32 m0, s46
	v_lshl_add_u64 v[220:221], s[42:43], 0, v[150:151]
	ds_read_b128 v[178:181], v161 offset:32768
	ds_read_b128 v[182:185], v161 offset:33792
	ds_read_b128 v[186:189], v161 offset:34816
	ds_read_b128 v[190:193], v161 offset:35840
	ds_read_b128 v[200:203], v161 offset:36864
	ds_read_b128 v[204:207], v161 offset:37888
	ds_read_b128 v[208:211], v161 offset:38912
	ds_read_b128 v[212:215], v161 offset:39936
	global_load_lds_dwordx4 v[220:221], off
	v_lshl_add_u64 v[220:221], s[42:43], 0, v[148:149]
	s_mov_b32 m0, s47
	s_nop 0
	global_load_lds_dwordx4 v[220:221], off
	s_waitcnt vmcnt(8)
	s_waitcnt lgkmcnt(0)
	s_barrier
	s_waitcnt lgkmcnt(0)
	v_mfma_i32_16x16x64_i8 v[142:145], v[90:93], v[178:181], v[142:145]
	v_mfma_i32_16x16x64_i8 v[142:145], v[94:97], v[182:185], v[142:145]
	v_mfma_i32_16x16x64_i8 v[126:129], v[90:93], v[186:189], v[126:129]
	v_mfma_i32_16x16x64_i8 v[126:129], v[94:97], v[190:193], v[126:129]
	v_mfma_i32_16x16x64_i8 v[102:105], v[90:93], v[200:203], v[102:105]
	v_mfma_i32_16x16x64_i8 v[102:105], v[94:97], v[204:207], v[102:105]
	v_mfma_i32_16x16x64_i8 v[78:81], v[90:93], v[208:211], v[78:81]
	v_mfma_i32_16x16x64_i8 v[78:81], v[94:97], v[212:215], v[78:81]
	v_mfma_i32_16x16x64_i8 v[138:141], v[106:109], v[178:181], v[138:141]
	v_mfma_i32_16x16x64_i8 v[138:141], v[114:117], v[182:185], v[138:141]
	v_mfma_i32_16x16x64_i8 v[122:125], v[106:109], v[186:189], v[122:125]
	v_mfma_i32_16x16x64_i8 v[122:125], v[114:117], v[190:193], v[122:125]
	v_mfma_i32_16x16x64_i8 v[98:101], v[106:109], v[200:203], v[98:101]
	v_mfma_i32_16x16x64_i8 v[98:101], v[114:117], v[204:207], v[98:101]
	v_mfma_i32_16x16x64_i8 v[74:77], v[106:109], v[208:211], v[74:77]
	v_mfma_i32_16x16x64_i8 v[74:77], v[114:117], v[212:215], v[74:77]
	v_mfma_i32_16x16x64_i8 v[134:137], v[162:165], v[178:181], v[134:137]
	v_mfma_i32_16x16x64_i8 v[134:137], v[166:169], v[182:185], v[134:137]
	v_mfma_i32_16x16x64_i8 v[118:121], v[162:165], v[186:189], v[118:121]
	v_mfma_i32_16x16x64_i8 v[118:121], v[166:169], v[190:193], v[118:121]
	v_mfma_i32_16x16x64_i8 v[86:89], v[162:165], v[200:203], v[86:89]
	v_mfma_i32_16x16x64_i8 v[86:89], v[166:169], v[204:207], v[86:89]
	v_mfma_i32_16x16x64_i8 v[70:73], v[162:165], v[208:211], v[70:73]
	v_mfma_i32_16x16x64_i8 v[70:73], v[166:169], v[212:215], v[70:73]
	v_mfma_i32_16x16x64_i8 v[130:133], v[170:173], v[178:181], v[130:133]
	v_mfma_i32_16x16x64_i8 v[130:133], v[174:177], v[182:185], v[130:133]
	v_mfma_i32_16x16x64_i8 v[110:113], v[170:173], v[186:189], v[110:113]
	v_mfma_i32_16x16x64_i8 v[110:113], v[174:177], v[190:193], v[110:113]
	v_mfma_i32_16x16x64_i8 v[82:85], v[170:173], v[200:203], v[82:85]
	v_mfma_i32_16x16x64_i8 v[82:85], v[174:177], v[204:207], v[82:85]
	v_mfma_i32_16x16x64_i8 v[66:69], v[170:173], v[208:211], v[66:69]
	v_mfma_i32_16x16x64_i8 v[66:69], v[174:177], v[212:215], v[66:69]
	s_barrier
	s_add_i32 s42, s66, s9
	v_lshl_add_u64 v[158:159], v[158:159], 0, s[12:13]
	s_mov_b32 m0, s42
	ds_read_b128 v[178:181], v161 offset:49152
	ds_read_b128 v[182:185], v161 offset:50176
	ds_read_b128 v[186:189], v161 offset:51200
	ds_read_b128 v[190:193], v161 offset:52224
	ds_read_b128 v[200:203], v161 offset:53248
	ds_read_b128 v[204:207], v161 offset:54272
	ds_read_b128 v[208:211], v161 offset:55296
	ds_read_b128 v[212:215], v161 offset:56320
	global_load_lds_dwordx4 v[158:159], off
	s_add_i32 m0, s42, 0x2000
	s_add_u32 s34, s34, 0x80080
	v_lshl_add_u64 v[158:159], v[194:195], 0, s[12:13]
	s_addc_u32 s35, s35, 0
	s_add_i32 s42, s67, s9
	global_load_lds_dwordx4 v[158:159], off
	v_lshl_add_u64 v[158:159], s[34:35], 0, v[0:1]
	s_mov_b32 m0, s42
	s_nop 0
	global_load_lds_dwordx4 v[158:159], off
	v_lshl_add_u64 v[158:159], s[34:35], 0, v[146:147]
	s_add_i32 m0, s42, 0x2000
	s_nop 0
	global_load_lds_dwordx4 v[158:159], off
	v_lshl_add_u64 v[158:159], v[216:217], 0, s[12:13]
	s_mov_b32 m0, s50
	s_nop 0
	global_load_lds_dwordx4 v[158:159], off
	v_lshl_add_u64 v[158:159], v[218:219], 0, s[12:13]
	s_mov_b32 m0, s51
	s_nop 0
	global_load_lds_dwordx4 v[158:159], off
	s_waitcnt vmcnt(8)
	s_waitcnt lgkmcnt(0)
	s_barrier
	s_waitcnt lgkmcnt(0)
	v_mfma_i32_16x16x64_i8 v[62:65], v[90:93], v[178:181], v[62:65]
	v_mfma_i32_16x16x64_i8 v[62:65], v[94:97], v[182:185], v[62:65]
	v_mfma_i32_16x16x64_i8 v[46:49], v[90:93], v[186:189], v[46:49]
	v_mfma_i32_16x16x64_i8 v[46:49], v[94:97], v[190:193], v[46:49]
	v_mfma_i32_16x16x64_i8 v[30:33], v[90:93], v[200:203], v[30:33]
	v_mfma_i32_16x16x64_i8 v[30:33], v[94:97], v[204:207], v[30:33]
	v_mfma_i32_16x16x64_i8 v[14:17], v[90:93], v[208:211], v[14:17]
	v_mfma_i32_16x16x64_i8 v[14:17], v[94:97], v[212:215], v[14:17]
	v_mfma_i32_16x16x64_i8 v[58:61], v[106:109], v[178:181], v[58:61]
	v_mfma_i32_16x16x64_i8 v[58:61], v[114:117], v[182:185], v[58:61]
	v_mfma_i32_16x16x64_i8 v[42:45], v[106:109], v[186:189], v[42:45]
	v_mfma_i32_16x16x64_i8 v[42:45], v[114:117], v[190:193], v[42:45]
	v_mfma_i32_16x16x64_i8 v[26:29], v[106:109], v[200:203], v[26:29]
	v_mfma_i32_16x16x64_i8 v[26:29], v[114:117], v[204:207], v[26:29]
	v_mfma_i32_16x16x64_i8 v[10:13], v[106:109], v[208:211], v[10:13]
	v_mfma_i32_16x16x64_i8 v[10:13], v[114:117], v[212:215], v[10:13]
	v_mfma_i32_16x16x64_i8 v[54:57], v[162:165], v[178:181], v[54:57]
	v_mfma_i32_16x16x64_i8 v[54:57], v[166:169], v[182:185], v[54:57]
	v_mfma_i32_16x16x64_i8 v[38:41], v[162:165], v[186:189], v[38:41]
	v_mfma_i32_16x16x64_i8 v[38:41], v[166:169], v[190:193], v[38:41]
	v_mfma_i32_16x16x64_i8 v[22:25], v[162:165], v[200:203], v[22:25]
	v_mfma_i32_16x16x64_i8 v[22:25], v[166:169], v[204:207], v[22:25]
	v_mfma_i32_16x16x64_i8 v[6:9], v[162:165], v[208:211], v[6:9]
	v_mfma_i32_16x16x64_i8 v[6:9], v[166:169], v[212:215], v[6:9]
	v_mfma_i32_16x16x64_i8 v[50:53], v[170:173], v[178:181], v[50:53]
	v_mfma_i32_16x16x64_i8 v[50:53], v[174:177], v[182:185], v[50:53]
	v_mfma_i32_16x16x64_i8 v[34:37], v[170:173], v[186:189], v[34:37]
	v_mfma_i32_16x16x64_i8 v[34:37], v[174:177], v[190:193], v[34:37]
	v_mfma_i32_16x16x64_i8 v[18:21], v[170:173], v[200:203], v[18:21]
	v_mfma_i32_16x16x64_i8 v[18:21], v[174:177], v[204:207], v[18:21]
	v_mfma_i32_16x16x64_i8 v[2:5], v[170:173], v[208:211], v[2:5]
	v_mfma_i32_16x16x64_i8 v[2:5], v[174:177], v[212:215], v[2:5]
	s_barrier
	s_add_i32 s57, s57, 2
	s_add_u32 s30, s30, 0x100
	s_addc_u32 s31, s31, 0
	s_add_u32 s55, s55, 0x100
	s_addc_u32 s56, s56, 0
	s_cmp_gt_u32 s57, 29
	s_cbranch_scc0 .LBB0_779
	s_and_b64 vcc, exec, s[20:21]
	s_mov_b32 s54, 0x5c401000
	s_cbranch_vccz .LBB0_782
	s_barrier

.LBB0_801:
	s_add_u32 s34, s30, 0xfff00080
	s_addc_u32 s35, s31, -1
	s_add_i32 s54, 0, 0x10000
	s_cmp_eq_u32 s53, 60
	s_cselect_b32 s41, s25, s35
	s_cselect_b32 s40, s49, s34
	s_cselect_b32 s35, s23, s52
	s_cselect_b32 s34, s50, s51
	s_add_i32 s56, 0, 0x14000
	v_add_u32_e32 v156, s54, v141
	v_add_u32_e32 v172, s56, v141
	ds_read_b128 v[144:147], v156
	ds_read_b128 v[148:151], v156 offset:1024
	ds_read_b128 v[152:155], v156 offset:2048
	ds_read_b128 v[156:159], v156 offset:3072
	ds_read_b128 v[160:163], v172
	ds_read_b128 v[164:167], v172 offset:1024
	ds_read_b128 v[168:171], v172 offset:2048
	ds_read_b128 v[172:175], v172 offset:3072
	v_lshl_add_u64 v[212:213], s[30:31], 0, v[136:137]
	s_add_i32 m0, s14, 0xc000
	ds_read_b128 v[176:179], v143
	ds_read_b128 v[180:183], v143 offset:1024
	ds_read_b128 v[184:187], v143 offset:2048
	ds_read_b128 v[188:191], v143 offset:3072
	ds_read_b128 v[192:195], v143 offset:4096
	ds_read_b128 v[200:203], v143 offset:5120
	ds_read_b128 v[204:207], v143 offset:6144
	ds_read_b128 v[208:211], v143 offset:7168
	global_load_lds_dwordx4 v[212:213], off
	v_lshl_add_u64 v[212:213], s[30:31], 0, v[138:139]
	s_add_i32 m0, s14, 0xe000
	s_nop 0
	global_load_lds_dwordx4 v[212:213], off
	s_waitcnt vmcnt(8)
	s_waitcnt lgkmcnt(0)
	s_barrier
	s_waitcnt lgkmcnt(0)
	v_mfma_f32_16x16x32_bf16 v[126:129], v[144:147], v[176:179], v[126:129]
	v_mfma_f32_16x16x32_bf16 v[126:129], v[148:151], v[180:183], v[126:129]
	v_mfma_f32_16x16x32_bf16 v[118:121], v[144:147], v[184:187], v[118:121]
	v_mfma_f32_16x16x32_bf16 v[118:121], v[148:151], v[188:191], v[118:121]
	v_mfma_f32_16x16x32_bf16 v[102:105], v[144:147], v[192:195], v[102:105]
	v_mfma_f32_16x16x32_bf16 v[102:105], v[148:151], v[200:203], v[102:105]
	v_mfma_f32_16x16x32_bf16 v[86:89], v[144:147], v[204:207], v[86:89]
	v_mfma_f32_16x16x32_bf16 v[86:89], v[148:151], v[208:211], v[86:89]
	v_mfma_f32_16x16x32_bf16 v[122:125], v[152:155], v[176:179], v[122:125]
	v_mfma_f32_16x16x32_bf16 v[122:125], v[156:159], v[180:183], v[122:125]
	v_mfma_f32_16x16x32_bf16 v[114:117], v[152:155], v[184:187], v[114:117]
	v_mfma_f32_16x16x32_bf16 v[114:117], v[156:159], v[188:191], v[114:117]
	v_mfma_f32_16x16x32_bf16 v[98:101], v[152:155], v[192:195], v[98:101]
	v_mfma_f32_16x16x32_bf16 v[98:101], v[156:159], v[200:203], v[98:101]
	v_mfma_f32_16x16x32_bf16 v[82:85], v[152:155], v[204:207], v[82:85]
	v_mfma_f32_16x16x32_bf16 v[82:85], v[156:159], v[208:211], v[82:85]
	v_mfma_f32_16x16x32_bf16 v[110:113], v[160:163], v[176:179], v[110:113]
	v_mfma_f32_16x16x32_bf16 v[110:113], v[164:167], v[180:183], v[110:113]
	v_mfma_f32_16x16x32_bf16 v[94:97], v[160:163], v[184:187], v[94:97]
	v_mfma_f32_16x16x32_bf16 v[94:97], v[164:167], v[188:191], v[94:97]
	v_mfma_f32_16x16x32_bf16 v[78:81], v[160:163], v[192:195], v[78:81]
	v_mfma_f32_16x16x32_bf16 v[78:81], v[164:167], v[200:203], v[78:81]
	v_mfma_f32_16x16x32_bf16 v[70:73], v[160:163], v[204:207], v[70:73]
	v_mfma_f32_16x16x32_bf16 v[70:73], v[164:167], v[208:211], v[70:73]
	v_mfma_f32_16x16x32_bf16 v[106:109], v[168:171], v[176:179], v[106:109]
	v_mfma_f32_16x16x32_bf16 v[106:109], v[172:175], v[180:183], v[106:109]
	v_mfma_f32_16x16x32_bf16 v[90:93], v[168:171], v[184:187], v[90:93]
	v_mfma_f32_16x16x32_bf16 v[90:93], v[172:175], v[188:191], v[90:93]
	v_mfma_f32_16x16x32_bf16 v[74:77], v[168:171], v[192:195], v[74:77]
	v_mfma_f32_16x16x32_bf16 v[74:77], v[172:175], v[200:203], v[74:77]
	v_mfma_f32_16x16x32_bf16 v[66:69], v[168:171], v[204:207], v[66:69]
	v_mfma_f32_16x16x32_bf16 v[66:69], v[172:175], v[208:211], v[66:69]
	s_barrier
	s_add_i32 s54, s54, s9
	v_lshl_add_u64 v[212:213], s[34:35], 0, v[0:1]
	s_mov_b32 m0, s54
	ds_read_b128 v[176:179], v143 offset:16384
	ds_read_b128 v[180:183], v143 offset:17408
	ds_read_b128 v[184:187], v143 offset:18432
	ds_read_b128 v[188:191], v143 offset:19456
	ds_read_b128 v[192:195], v143 offset:20480
	ds_read_b128 v[200:203], v143 offset:21504
	ds_read_b128 v[204:207], v143 offset:22528
	ds_read_b128 v[208:211], v143 offset:23552
	global_load_lds_dwordx4 v[212:213], off
	s_add_i32 m0, s54, 0x2000
	s_add_u32 s54, s34, 0x100000
	v_lshl_add_u64 v[214:215], s[34:35], 0, v[130:131]
	s_addc_u32 s55, s35, 0
	s_add_i32 s56, s56, s9
	global_load_lds_dwordx4 v[214:215], off
	v_lshl_add_u64 v[216:217], s[54:55], 0, v[0:1]
	s_mov_b32 m0, s56
	v_lshl_add_u64 v[218:219], s[40:41], 0, v[132:133]
	global_load_lds_dwordx4 v[216:217], off
	v_lshl_add_u64 v[216:217], s[54:55], 0, v[130:131]
	s_add_i32 m0, s56, 0x2000
	s_nop 0
	global_load_lds_dwordx4 v[216:217], off
	v_lshl_add_u64 v[216:217], s[40:41], 0, v[134:135]
	s_mov_b32 m0, s14
	s_nop 0
	global_load_lds_dwordx4 v[216:217], off
	s_mov_b32 m0, s15
	s_nop 0
	global_load_lds_dwordx4 v[218:219], off
	s_waitcnt vmcnt(8)
	s_waitcnt lgkmcnt(0)
	s_barrier
	s_waitcnt lgkmcnt(0)
	v_mfma_f32_16x16x32_bf16 v[62:65], v[144:147], v[176:179], v[62:65]
	v_mfma_f32_16x16x32_bf16 v[62:65], v[148:151], v[180:183], v[62:65]
	v_mfma_f32_16x16x32_bf16 v[54:57], v[144:147], v[184:187], v[54:57]
	v_mfma_f32_16x16x32_bf16 v[54:57], v[148:151], v[188:191], v[54:57]
	v_mfma_f32_16x16x32_bf16 v[38:41], v[144:147], v[192:195], v[38:41]
	v_mfma_f32_16x16x32_bf16 v[38:41], v[148:151], v[200:203], v[38:41]
	v_mfma_f32_16x16x32_bf16 v[22:25], v[144:147], v[204:207], v[22:25]
	v_mfma_f32_16x16x32_bf16 v[22:25], v[148:151], v[208:211], v[22:25]
	v_mfma_f32_16x16x32_bf16 v[58:61], v[152:155], v[176:179], v[58:61]
	v_mfma_f32_16x16x32_bf16 v[58:61], v[156:159], v[180:183], v[58:61]
	v_mfma_f32_16x16x32_bf16 v[50:53], v[152:155], v[184:187], v[50:53]
	v_mfma_f32_16x16x32_bf16 v[50:53], v[156:159], v[188:191], v[50:53]
	v_mfma_f32_16x16x32_bf16 v[34:37], v[152:155], v[192:195], v[34:37]
	v_mfma_f32_16x16x32_bf16 v[34:37], v[156:159], v[200:203], v[34:37]
	v_mfma_f32_16x16x32_bf16 v[18:21], v[152:155], v[204:207], v[18:21]
	v_mfma_f32_16x16x32_bf16 v[18:21], v[156:159], v[208:211], v[18:21]
	v_mfma_f32_16x16x32_bf16 v[46:49], v[160:163], v[176:179], v[46:49]
	v_mfma_f32_16x16x32_bf16 v[46:49], v[164:167], v[180:183], v[46:49]
	v_mfma_f32_16x16x32_bf16 v[30:33], v[160:163], v[184:187], v[30:33]
	v_mfma_f32_16x16x32_bf16 v[30:33], v[164:167], v[188:191], v[30:33]
	v_mfma_f32_16x16x32_bf16 v[14:17], v[160:163], v[192:195], v[14:17]
	v_mfma_f32_16x16x32_bf16 v[14:17], v[164:167], v[200:203], v[14:17]
	v_mfma_f32_16x16x32_bf16 v[6:9], v[160:163], v[204:207], v[6:9]
	v_mfma_f32_16x16x32_bf16 v[6:9], v[164:167], v[208:211], v[6:9]
	v_mfma_f32_16x16x32_bf16 v[42:45], v[168:171], v[176:179], v[42:45]
	v_mfma_f32_16x16x32_bf16 v[42:45], v[172:175], v[180:183], v[42:45]
	v_mfma_f32_16x16x32_bf16 v[26:29], v[168:171], v[184:187], v[26:29]
	v_mfma_f32_16x16x32_bf16 v[26:29], v[172:175], v[188:191], v[26:29]
	v_mfma_f32_16x16x32_bf16 v[10:13], v[168:171], v[192:195], v[10:13]
	v_mfma_f32_16x16x32_bf16 v[10:13], v[172:175], v[200:203], v[10:13]
	v_mfma_f32_16x16x32_bf16 v[2:5], v[168:171], v[204:207], v[2:5]
	v_mfma_f32_16x16x32_bf16 v[2:5], v[172:175], v[208:211], v[2:5]
	s_barrier
	s_add_i32 s54, 0, 0x18000
	s_add_i32 s55, 0, 0x1c000
	v_add_u32_e32 v156, s54, v141
	v_add_u32_e32 v172, s55, v141
	ds_read_b128 v[144:147], v156
	ds_read_b128 v[148:151], v156 offset:1024
	ds_read_b128 v[152:155], v156 offset:2048
	ds_read_b128 v[156:159], v156 offset:3072
	ds_read_b128 v[160:163], v172
	ds_read_b128 v[164:167], v172 offset:1024
	ds_read_b128 v[168:171], v172 offset:2048
	ds_read_b128 v[172:175], v172 offset:3072
	s_add_u32 s40, s40, 0x100000
	s_addc_u32 s41, s41, 0
	s_mov_b32 m0, s18
	v_lshl_add_u64 v[220:221], s[40:41], 0, v[134:135]
	ds_read_b128 v[176:179], v143 offset:32768
	ds_read_b128 v[180:183], v143 offset:33792
	ds_read_b128 v[184:187], v143 offset:34816
	ds_read_b128 v[188:191], v143 offset:35840
	ds_read_b128 v[192:195], v143 offset:36864
	ds_read_b128 v[200:203], v143 offset:37888
	ds_read_b128 v[204:207], v143 offset:38912
	ds_read_b128 v[208:211], v143 offset:39936
	global_load_lds_dwordx4 v[220:221], off
	v_lshl_add_u64 v[220:221], s[40:41], 0, v[132:133]
	s_mov_b32 m0, s19
	s_nop 0
	global_load_lds_dwordx4 v[220:221], off
	s_waitcnt vmcnt(8)
	s_waitcnt lgkmcnt(0)
	s_barrier
	s_waitcnt lgkmcnt(0)
	v_mfma_f32_16x16x32_bf16 v[126:129], v[144:147], v[176:179], v[126:129]
	v_mfma_f32_16x16x32_bf16 v[126:129], v[148:151], v[180:183], v[126:129]
	v_mfma_f32_16x16x32_bf16 v[118:121], v[144:147], v[184:187], v[118:121]
	v_mfma_f32_16x16x32_bf16 v[118:121], v[148:151], v[188:191], v[118:121]
	v_mfma_f32_16x16x32_bf16 v[102:105], v[144:147], v[192:195], v[102:105]
	v_mfma_f32_16x16x32_bf16 v[102:105], v[148:151], v[200:203], v[102:105]
	v_mfma_f32_16x16x32_bf16 v[86:89], v[144:147], v[204:207], v[86:89]
	v_mfma_f32_16x16x32_bf16 v[86:89], v[148:151], v[208:211], v[86:89]
	v_mfma_f32_16x16x32_bf16 v[122:125], v[152:155], v[176:179], v[122:125]
	v_mfma_f32_16x16x32_bf16 v[122:125], v[156:159], v[180:183], v[122:125]
	v_mfma_f32_16x16x32_bf16 v[114:117], v[152:155], v[184:187], v[114:117]
	v_mfma_f32_16x16x32_bf16 v[114:117], v[156:159], v[188:191], v[114:117]
	v_mfma_f32_16x16x32_bf16 v[98:101], v[152:155], v[192:195], v[98:101]
	v_mfma_f32_16x16x32_bf16 v[98:101], v[156:159], v[200:203], v[98:101]
	v_mfma_f32_16x16x32_bf16 v[82:85], v[152:155], v[204:207], v[82:85]
	v_mfma_f32_16x16x32_bf16 v[82:85], v[156:159], v[208:211], v[82:85]
	v_mfma_f32_16x16x32_bf16 v[110:113], v[160:163], v[176:179], v[110:113]
	v_mfma_f32_16x16x32_bf16 v[110:113], v[164:167], v[180:183], v[110:113]
	v_mfma_f32_16x16x32_bf16 v[94:97], v[160:163], v[184:187], v[94:97]
	v_mfma_f32_16x16x32_bf16 v[94:97], v[164:167], v[188:191], v[94:97]
	v_mfma_f32_16x16x32_bf16 v[78:81], v[160:163], v[192:195], v[78:81]
	v_mfma_f32_16x16x32_bf16 v[78:81], v[164:167], v[200:203], v[78:81]
	v_mfma_f32_16x16x32_bf16 v[70:73], v[160:163], v[204:207], v[70:73]
	v_mfma_f32_16x16x32_bf16 v[70:73], v[164:167], v[208:211], v[70:73]
	v_mfma_f32_16x16x32_bf16 v[106:109], v[168:171], v[176:179], v[106:109]
	v_mfma_f32_16x16x32_bf16 v[106:109], v[172:175], v[180:183], v[106:109]
	v_mfma_f32_16x16x32_bf16 v[90:93], v[168:171], v[184:187], v[90:93]
	v_mfma_f32_16x16x32_bf16 v[90:93], v[172:175], v[188:191], v[90:93]
	v_mfma_f32_16x16x32_bf16 v[74:77], v[168:171], v[192:195], v[74:77]
	v_mfma_f32_16x16x32_bf16 v[74:77], v[172:175], v[200:203], v[74:77]
	v_mfma_f32_16x16x32_bf16 v[66:69], v[168:171], v[204:207], v[66:69]
	v_mfma_f32_16x16x32_bf16 v[66:69], v[172:175], v[208:211], v[66:69]
	s_barrier
	s_add_i32 s40, s54, s9
	v_lshl_add_u64 v[212:213], v[212:213], 0, s[12:13]
	s_mov_b32 m0, s40
	ds_read_b128 v[176:179], v143 offset:49152
	ds_read_b128 v[180:183], v143 offset:50176
	ds_read_b128 v[184:187], v143 offset:51200
	ds_read_b128 v[188:191], v143 offset:52224
	ds_read_b128 v[192:195], v143 offset:53248
	ds_read_b128 v[200:203], v143 offset:54272
	ds_read_b128 v[204:207], v143 offset:55296
	ds_read_b128 v[208:211], v143 offset:56320
	global_load_lds_dwordx4 v[212:213], off
	s_add_i32 m0, s40, 0x2000
	s_add_u32 s34, s34, 0x100080
	v_lshl_add_u64 v[212:213], v[214:215], 0, s[12:13]
	s_addc_u32 s35, s35, 0
	s_add_i32 s40, s55, s9
	global_load_lds_dwordx4 v[212:213], off
	v_lshl_add_u64 v[212:213], s[34:35], 0, v[0:1]
	s_mov_b32 m0, s40
	s_nop 0
	global_load_lds_dwordx4 v[212:213], off
	v_lshl_add_u64 v[212:213], s[34:35], 0, v[130:131]
	s_add_i32 m0, s40, 0x2000
	s_nop 0
	global_load_lds_dwordx4 v[212:213], off
	v_lshl_add_u64 v[212:213], v[216:217], 0, s[12:13]
	s_mov_b32 m0, s42
	s_nop 0
	global_load_lds_dwordx4 v[212:213], off
	v_lshl_add_u64 v[212:213], v[218:219], 0, s[12:13]
	s_mov_b32 m0, s43
	s_nop 0
	global_load_lds_dwordx4 v[212:213], off
	s_waitcnt vmcnt(8)
	s_waitcnt lgkmcnt(0)
	s_barrier
	s_waitcnt lgkmcnt(0)
	v_mfma_f32_16x16x32_bf16 v[62:65], v[144:147], v[176:179], v[62:65]
	v_mfma_f32_16x16x32_bf16 v[62:65], v[148:151], v[180:183], v[62:65]
	v_mfma_f32_16x16x32_bf16 v[54:57], v[144:147], v[184:187], v[54:57]
	v_mfma_f32_16x16x32_bf16 v[54:57], v[148:151], v[188:191], v[54:57]
	v_mfma_f32_16x16x32_bf16 v[38:41], v[144:147], v[192:195], v[38:41]
	v_mfma_f32_16x16x32_bf16 v[38:41], v[148:151], v[200:203], v[38:41]
	v_mfma_f32_16x16x32_bf16 v[22:25], v[144:147], v[204:207], v[22:25]
	v_mfma_f32_16x16x32_bf16 v[22:25], v[148:151], v[208:211], v[22:25]
	v_mfma_f32_16x16x32_bf16 v[58:61], v[152:155], v[176:179], v[58:61]
	v_mfma_f32_16x16x32_bf16 v[58:61], v[156:159], v[180:183], v[58:61]
	v_mfma_f32_16x16x32_bf16 v[50:53], v[152:155], v[184:187], v[50:53]
	v_mfma_f32_16x16x32_bf16 v[50:53], v[156:159], v[188:191], v[50:53]
	v_mfma_f32_16x16x32_bf16 v[34:37], v[152:155], v[192:195], v[34:37]
	v_mfma_f32_16x16x32_bf16 v[34:37], v[156:159], v[200:203], v[34:37]
	v_mfma_f32_16x16x32_bf16 v[18:21], v[152:155], v[204:207], v[18:21]
	v_mfma_f32_16x16x32_bf16 v[18:21], v[156:159], v[208:211], v[18:21]
	v_mfma_f32_16x16x32_bf16 v[46:49], v[160:163], v[176:179], v[46:49]
	v_mfma_f32_16x16x32_bf16 v[46:49], v[164:167], v[180:183], v[46:49]
	v_mfma_f32_16x16x32_bf16 v[30:33], v[160:163], v[184:187], v[30:33]
	v_mfma_f32_16x16x32_bf16 v[30:33], v[164:167], v[188:191], v[30:33]
	v_mfma_f32_16x16x32_bf16 v[14:17], v[160:163], v[192:195], v[14:17]
	v_mfma_f32_16x16x32_bf16 v[14:17], v[164:167], v[200:203], v[14:17]
	v_mfma_f32_16x16x32_bf16 v[6:9], v[160:163], v[204:207], v[6:9]
	v_mfma_f32_16x16x32_bf16 v[6:9], v[164:167], v[208:211], v[6:9]
	v_mfma_f32_16x16x32_bf16 v[42:45], v[168:171], v[176:179], v[42:45]
	v_mfma_f32_16x16x32_bf16 v[42:45], v[172:175], v[180:183], v[42:45]
	v_mfma_f32_16x16x32_bf16 v[26:29], v[168:171], v[184:187], v[26:29]
	v_mfma_f32_16x16x32_bf16 v[26:29], v[172:175], v[188:191], v[26:29]
	v_mfma_f32_16x16x32_bf16 v[10:13], v[168:171], v[192:195], v[10:13]
	v_mfma_f32_16x16x32_bf16 v[10:13], v[172:175], v[200:203], v[10:13]
	v_mfma_f32_16x16x32_bf16 v[2:5], v[168:171], v[204:207], v[2:5]
	v_mfma_f32_16x16x32_bf16 v[2:5], v[172:175], v[208:211], v[2:5]
	s_barrier
	s_add_i32 s53, s53, 2
	s_add_u32 s30, s30, 0x100
	s_addc_u32 s31, s31, 0
	s_add_u32 s51, s51, 0x100
	s_addc_u32 s52, s52, 0
	s_cmp_gt_u32 s53, 61
	s_cbranch_scc0 .LBB0_801
	s_and_b64 vcc, exec, s[20:21]
	s_cbranch_vccz .LBB0_804
	s_barrier
